# K-loops: no s_setprio toggling and the duplicated lgkmcnt(0) wait before each MFMA block removed
# baseline (speedup 1.0000x reference)
; #define G_STAGE(bufoff, gbase, voff) do { _Pragma("unroll") for (int _i = 0; _i < 2; ++_i) \
;         __builtin_amdgcn_global_load_lds((const unsigned*)((const char*)(gbase) + (voff)[_i]), (LAS unsigned*)(lds + (bufoff) + ldsw + _i * 8192), 16, 0, 0); } while (0)
; #define G_WAIT_V(n) asm volatile("s_waitcnt vmcnt(" #n ")" ::: "memory")
; #define G_WAIT_L(n) asm volatile("s_waitcnt lgkmcnt(" #n ")" ::: "memory")
; #define G_BAR __builtin_amdgcn_s_barrier()
; #define G_SCHED __builtin_amdgcn_sched_barrier(0)
; template <int MODE  , class Epi, class Sched>
; __device__ __forceinline__ void gemm_phase(LAS unsigned char* lds, const GemmDesc g, const Sched& S, const Epi& E) {
;     ...
;         for (int t = 0; t < nt; t += 2) {
;             const bool last = (t == nt - 2);
;             const char* a1 = cA + (size_t)(t + 1) * kstep;
;             const char* a2 = last ? nA : cA + (size_t)(t + 2) * kstep; const char* b2 = last ? nB : cB + (size_t)(t + 2) * kstep;
;             const char* a3 = a2 + kstep; const char* b3 = b2 + kstep;
;             G_LDB(B0, 0, 0); G_SCHED; G_LDA(At, 0, 0); G_STAGE(G_SA(1, 1), a1 + hstepA, voffA);
;             G_WAIT_L(8); G_BAR; G_WAIT_L(0); G_MMA(0, 0, At, B0); G_BAR; G_SCHED;
;             G_LDB(B1, 0, 1); G_STAGE(G_SB(0, 0), b2, voffB);
;             G_BAR; G_WAIT_L(0); G_MMA(0, 1, At, B1); G_BAR;
;             G_LDA(At, 0, 1); G_STAGE(G_SA(0, 0), a2, voffA);
;             G_BAR; G_WAIT_L(0); G_MMA(1, 0, At, B0); G_BAR; G_SCHED;
;             G_STAGE(G_SB(0, 1), b2 + hstepB, voffB);
;             G_WAIT_V(6); G_BAR; G_MMA(1, 1, At, B1); G_BAR;
.Lnodb_p1c:
.LBB0_527:
	s_add_u32 s40, s34, 0x100
	s_addc_u32 s41, s35, 0
	s_cmp_eq_u32 s77, 12
	s_cselect_b32 s47, s21, s41
	s_cselect_b32 s46, s20, s40
	s_cselect_b32 s45, s3, s76
	s_cselect_b32 s44, s2, s72
	s_mov_b32 m0, s64
	s_add_u32 s98, s34, 0x44080
	s_addc_u32 s99, s35, 0
	ds_read_b128 v[162:165], v194
	ds_read_b128 v[166:169], v194 offset:1024
	ds_read_b128 v[170:173], v194 offset:2048
	ds_read_b128 v[174:177], v194 offset:3072
	ds_read_b128 v[178:181], v194 offset:4096
	ds_read_b128 v[182:185], v194 offset:5120
	ds_read_b128 v[186:189], v194 offset:6144
	ds_read_b128 v[198:201], v194 offset:7168
	global_load_lds_dwordx4 v146, s[98:99]
	s_mov_b32 m0, s65
	s_nop 0
	global_load_lds_dwordx4 v150, s[98:99]
	s_waitcnt lgkmcnt(8)
	s_barrier
	s_waitcnt lgkmcnt(0)
	v_mfma_i32_16x16x64_i8 v[134:137], v[232:235], v[162:165], v[134:137]
	v_mfma_i32_16x16x64_i8 v[130:133], v[240:243], v[162:165], v[130:133]
	v_mfma_i32_16x16x64_i8 v[118:121], v[232:235], v[170:173], v[118:121]
	v_mfma_i32_16x16x64_i8 v[114:117], v[240:243], v[170:173], v[114:117]
	v_mfma_i32_16x16x64_i8 v[102:105], v[232:235], v[178:181], v[102:105]
	v_mfma_i32_16x16x64_i8 v[98:101], v[240:243], v[178:181], v[98:101]
	v_mfma_i32_16x16x64_i8 v[86:89], v[232:235], v[186:189], v[86:89]
	v_mfma_i32_16x16x64_i8 v[82:85], v[240:243], v[186:189], v[82:85]
	v_mfma_i32_16x16x64_i8 v[134:137], v[236:239], v[166:169], v[134:137]
	v_mfma_i32_16x16x64_i8 v[130:133], v[244:247], v[166:169], v[130:133]
	v_mfma_i32_16x16x64_i8 v[118:121], v[236:239], v[174:177], v[118:121]
	v_mfma_i32_16x16x64_i8 v[114:117], v[244:247], v[174:177], v[114:117]
	v_mfma_i32_16x16x64_i8 v[102:105], v[236:239], v[182:185], v[102:105]
	v_mfma_i32_16x16x64_i8 v[98:101], v[244:247], v[182:185], v[98:101]
	v_mfma_i32_16x16x64_i8 v[86:89], v[236:239], v[198:201], v[86:89]
	v_mfma_i32_16x16x64_i8 v[82:85], v[244:247], v[198:201], v[82:85]
	s_barrier
	s_mov_b32 m0, s66
	ds_read_b128 v[202:205], v195
	ds_read_b128 v[206:209], v195 offset:1024
	ds_read_b128 v[210:213], v195 offset:2048
	ds_read_b128 v[214:217], v195 offset:3072
	global_load_lds_dwordx4 v148, s[44:45]
	s_mov_b32 m0, s67
	s_nop 0
	global_load_lds_dwordx4 v152, s[44:45]
	s_barrier
	s_waitcnt lgkmcnt(0)
	v_mfma_i32_16x16x64_i8 v[142:145], v[202:205], v[162:165], v[142:145]
	v_mfma_i32_16x16x64_i8 v[138:141], v[210:213], v[162:165], v[138:141]
	v_mfma_i32_16x16x64_i8 v[126:129], v[202:205], v[170:173], v[126:129]
	v_mfma_i32_16x16x64_i8 v[122:125], v[210:213], v[170:173], v[122:125]
	v_mfma_i32_16x16x64_i8 v[110:113], v[202:205], v[178:181], v[110:113]
	v_mfma_i32_16x16x64_i8 v[106:109], v[210:213], v[178:181], v[106:109]
	v_mfma_i32_16x16x64_i8 v[94:97], v[202:205], v[186:189], v[94:97]
	v_mfma_i32_16x16x64_i8 v[90:93], v[210:213], v[186:189], v[90:93]
	v_mfma_i32_16x16x64_i8 v[142:145], v[206:209], v[166:169], v[142:145]
	v_mfma_i32_16x16x64_i8 v[138:141], v[214:217], v[166:169], v[138:141]
	v_mfma_i32_16x16x64_i8 v[126:129], v[206:209], v[174:177], v[126:129]
	v_mfma_i32_16x16x64_i8 v[122:125], v[214:217], v[174:177], v[122:125]
	v_mfma_i32_16x16x64_i8 v[110:113], v[206:209], v[182:185], v[110:113]
	v_mfma_i32_16x16x64_i8 v[106:109], v[214:217], v[182:185], v[106:109]
	v_mfma_i32_16x16x64_i8 v[94:97], v[206:209], v[198:201], v[94:97]
	v_mfma_i32_16x16x64_i8 v[90:93], v[214:217], v[198:201], v[90:93]
	s_mov_b32 m0, s55
	s_barrier
	ds_read_b128 v[162:165], v194 offset:16384
	ds_read_b128 v[166:169], v194 offset:17408
	ds_read_b128 v[170:173], v194 offset:18432
	ds_read_b128 v[174:177], v194 offset:19456
	ds_read_b128 v[178:181], v194 offset:20480
	ds_read_b128 v[182:185], v194 offset:21504
	ds_read_b128 v[186:189], v194 offset:22528
	ds_read_b128 v[198:201], v194 offset:23552
	global_load_lds_dwordx4 v146, s[46:47]
	s_mov_b32 m0, s56
	s_nop 0
	global_load_lds_dwordx4 v150, s[46:47]
	s_barrier
	s_waitcnt lgkmcnt(0)
	v_mfma_i32_16x16x64_i8 v[70:73], v[232:235], v[162:165], v[70:73]
	v_mfma_i32_16x16x64_i8 v[66:69], v[240:243], v[162:165], v[66:69]
	v_mfma_i32_16x16x64_i8 v[54:57], v[232:235], v[170:173], v[54:57]
	v_mfma_i32_16x16x64_i8 v[50:53], v[240:243], v[170:173], v[50:53]
	v_mfma_i32_16x16x64_i8 v[22:25], v[232:235], v[178:181], v[22:25]
	v_mfma_i32_16x16x64_i8 v[18:21], v[240:243], v[178:181], v[18:21]
	v_mfma_i32_16x16x64_i8 v[6:9], v[232:235], v[186:189], v[6:9]
	v_mfma_i32_16x16x64_i8 v[2:5], v[240:243], v[186:189], v[2:5]
	v_mfma_i32_16x16x64_i8 v[70:73], v[236:239], v[166:169], v[70:73]
	v_mfma_i32_16x16x64_i8 v[66:69], v[244:247], v[166:169], v[66:69]
	v_mfma_i32_16x16x64_i8 v[54:57], v[236:239], v[174:177], v[54:57]
	v_mfma_i32_16x16x64_i8 v[50:53], v[244:247], v[174:177], v[50:53]
	v_mfma_i32_16x16x64_i8 v[22:25], v[236:239], v[182:185], v[22:25]
	v_mfma_i32_16x16x64_i8 v[18:21], v[244:247], v[182:185], v[18:21]
	v_mfma_i32_16x16x64_i8 v[6:9], v[236:239], v[198:201], v[6:9]
	v_mfma_i32_16x16x64_i8 v[2:5], v[244:247], v[198:201], v[2:5]
	s_barrier
	s_mov_b32 m0, s68
	s_add_u32 s0, s44, 0x44000
	s_addc_u32 s1, s45, 0
	global_load_lds_dwordx4 v148, s[0:1]
	s_mov_b32 m0, s69
	s_nop 0
	global_load_lds_dwordx4 v152, s[0:1]
	s_waitcnt vmcnt(6)
	s_barrier
; #define G_STAGE(bufoff, gbase, voff) do { _Pragma("unroll") for (int _i = 0; _i < 2; ++_i) \
;         __builtin_amdgcn_global_load_lds((const unsigned*)((const char*)(gbase) + (voff)[_i]), (LAS unsigned*)(lds + (bufoff) + ldsw + _i * 8192), 16, 0, 0); } while (0)
; #define G_WAIT_V(n) asm volatile("s_waitcnt vmcnt(" #n ")" ::: "memory")
; #define G_WAIT_L(n) asm volatile("s_waitcnt lgkmcnt(" #n ")" ::: "memory")
; #define G_BAR __builtin_amdgcn_s_barrier()
; #define G_SCHED __builtin_amdgcn_sched_barrier(0)
; template <int MODE  , class Epi, class Sched>
; __device__ __forceinline__ void gemm_phase(LAS unsigned char* lds, const GemmDesc g, const Sched& S, const Epi& E) {
;     ...
;             G_WAIT_V(6); G_BAR; G_MMA(1, 1, At, B1); G_BAR;
;             G_LDB(B0, 1, 0); G_SCHED; G_LDA(At, 1, 0); G_STAGE(G_SA(0, 1), a2 + hstepA, voffA);
;             G_WAIT_L(8); G_BAR; G_WAIT_L(0); G_MMA(0, 0, At, B0); G_BAR; G_SCHED;
;             G_LDB(B1, 1, 1); G_STAGE(G_SB(1, 0), b3, voffB);
;             G_BAR; G_WAIT_L(0); G_MMA(0, 1, At, B1); G_BAR;
;             G_LDA(At, 1, 1); G_STAGE(G_SA(1, 0), a3, voffA);
	v_mfma_i32_16x16x64_i8 v[30:33], v[202:205], v[178:181], v[30:33]
	v_mfma_i32_16x16x64_i8 v[26:29], v[210:213], v[178:181], v[26:29]
	v_mfma_i32_16x16x64_i8 v[14:17], v[202:205], v[186:189], v[14:17]
	v_mfma_i32_16x16x64_i8 v[10:13], v[210:213], v[186:189], v[10:13]
	v_mfma_i32_16x16x64_i8 v[34:37], v[202:205], v[162:165], v[78:81]
	v_mfma_i32_16x16x64_i8 v[38:41], v[210:213], v[162:165], v[74:77]
	v_mfma_i32_16x16x64_i8 v[42:45], v[202:205], v[170:173], v[62:65]
	v_mfma_i32_16x16x64_i8 v[46:49], v[210:213], v[170:173], v[58:61]
	v_mfma_i32_16x16x64_i8 v[30:33], v[206:209], v[182:185], v[30:33]
	v_mfma_i32_16x16x64_i8 v[26:29], v[214:217], v[182:185], v[26:29]
	v_mfma_i32_16x16x64_i8 v[14:17], v[206:209], v[198:201], v[14:17]
	v_mfma_i32_16x16x64_i8 v[10:13], v[214:217], v[198:201], v[10:13]
	v_mfma_i32_16x16x64_i8 v[34:37], v[206:209], v[166:169], v[34:37]
	v_mfma_i32_16x16x64_i8 v[38:41], v[214:217], v[166:169], v[38:41]
	v_mfma_i32_16x16x64_i8 v[42:45], v[206:209], v[174:177], v[42:45]
	v_mfma_i32_16x16x64_i8 v[46:49], v[214:217], v[174:177], v[46:49]
	s_add_i32 s10, 0, 0x18000
	v_add_u32_e32 v78, s10, v191
	s_barrier
	ds_read_b128 v[58:61], v78
	ds_read_b128 v[62:65], v78 offset:1024
	ds_read_b128 v[74:77], v78 offset:2048
	ds_read_b128 v[78:81], v78 offset:3072
	s_add_u32 s0, s46, 0x44000
	s_addc_u32 s1, s47, 0
	s_mov_b32 m0, s57
	ds_read_b128 v[162:165], v194 offset:32768
	ds_read_b128 v[166:169], v194 offset:33792
	ds_read_b128 v[170:173], v194 offset:34816
	ds_read_b128 v[174:177], v194 offset:35840
	ds_read_b128 v[178:181], v194 offset:36864
	ds_read_b128 v[182:185], v194 offset:37888
	ds_read_b128 v[186:189], v194 offset:38912
	ds_read_b128 v[198:201], v194 offset:39936
	global_load_lds_dwordx4 v146, s[0:1]
	s_mov_b32 m0, s58
	s_nop 0
	global_load_lds_dwordx4 v150, s[0:1]
	s_waitcnt lgkmcnt(8)
	s_barrier
	s_waitcnt lgkmcnt(0)
	v_mfma_i32_16x16x64_i8 v[134:137], v[58:61], v[162:165], v[134:137]
	v_mfma_i32_16x16x64_i8 v[130:133], v[74:77], v[162:165], v[130:133]
	v_mfma_i32_16x16x64_i8 v[118:121], v[58:61], v[170:173], v[118:121]
	v_mfma_i32_16x16x64_i8 v[114:117], v[74:77], v[170:173], v[114:117]
	v_mfma_i32_16x16x64_i8 v[102:105], v[58:61], v[178:181], v[102:105]
	v_mfma_i32_16x16x64_i8 v[98:101], v[74:77], v[178:181], v[98:101]
	v_mfma_i32_16x16x64_i8 v[86:89], v[58:61], v[186:189], v[86:89]
	v_mfma_i32_16x16x64_i8 v[82:85], v[74:77], v[186:189], v[82:85]
	v_mfma_i32_16x16x64_i8 v[134:137], v[62:65], v[166:169], v[134:137]
	v_mfma_i32_16x16x64_i8 v[130:133], v[78:81], v[166:169], v[130:133]
	v_mfma_i32_16x16x64_i8 v[118:121], v[62:65], v[174:177], v[118:121]
	v_mfma_i32_16x16x64_i8 v[114:117], v[78:81], v[174:177], v[114:117]
	v_mfma_i32_16x16x64_i8 v[102:105], v[62:65], v[182:185], v[102:105]
	v_mfma_i32_16x16x64_i8 v[98:101], v[78:81], v[182:185], v[98:101]
	v_mfma_i32_16x16x64_i8 v[86:89], v[62:65], v[198:201], v[86:89]
	v_mfma_i32_16x16x64_i8 v[82:85], v[78:81], v[198:201], v[82:85]
	s_barrier
	s_add_i32 s11, 0, 0x1c000
	s_add_i32 s0, s10, s54
	v_add_u32_e32 v154, s11, v191
	s_add_u32 s98, s44, 0x80
	s_addc_u32 s99, s45, 0
	s_mov_b32 m0, s0
	ds_read_b128 v[202:205], v154
	ds_read_b128 v[206:209], v154 offset:1024
	ds_read_b128 v[210:213], v154 offset:2048
	ds_read_b128 v[214:217], v154 offset:3072
	global_load_lds_dwordx4 v148, s[98:99]
	s_add_i32 m0, s0, 0x2000
	s_nop 0
	global_load_lds_dwordx4 v152, s[98:99]
	s_barrier
; #define G_STAGE(bufoff, gbase, voff) do { _Pragma("unroll") for (int _i = 0; _i < 2; ++_i) \
;         __builtin_amdgcn_global_load_lds((const unsigned*)((const char*)(gbase) + (voff)[_i]), (LAS unsigned*)(lds + (bufoff) + ldsw + _i * 8192), 16, 0, 0); } while (0)
; #define G_WAIT_V(n) asm volatile("s_waitcnt vmcnt(" #n ")" ::: "memory")
; #define G_WAIT_L(n) asm volatile("s_waitcnt lgkmcnt(" #n ")" ::: "memory")
; #define G_BAR __builtin_amdgcn_s_barrier()
; #define G_SCHED __builtin_amdgcn_sched_barrier(0)
; template <int MODE  , class Epi, class Sched>
; __device__ __forceinline__ void gemm_phase(LAS unsigned char* lds, const GemmDesc g, const Sched& S, const Epi& E) {
;     ...
;             G_LDA(At, 1, 1); G_STAGE(G_SA(1, 0), a3, voffA);
;             G_BAR; G_WAIT_L(0); G_MMA(1, 0, At, B0); G_BAR; G_SCHED;
;             G_STAGE(G_SB(1, 1), b3 + hstepB, voffB);
;             G_WAIT_V(6); G_BAR; G_MMA(1, 1, At, B1); G_BAR;
;         }
	s_waitcnt lgkmcnt(0)
	v_mfma_i32_16x16x64_i8 v[142:145], v[202:205], v[162:165], v[142:145]
	v_mfma_i32_16x16x64_i8 v[138:141], v[210:213], v[162:165], v[138:141]
	v_mfma_i32_16x16x64_i8 v[126:129], v[202:205], v[170:173], v[126:129]
	v_mfma_i32_16x16x64_i8 v[122:125], v[210:213], v[170:173], v[122:125]
	v_mfma_i32_16x16x64_i8 v[110:113], v[202:205], v[178:181], v[110:113]
	v_mfma_i32_16x16x64_i8 v[106:109], v[210:213], v[178:181], v[106:109]
	v_mfma_i32_16x16x64_i8 v[94:97], v[202:205], v[186:189], v[94:97]
	v_mfma_i32_16x16x64_i8 v[90:93], v[210:213], v[186:189], v[90:93]
	v_mfma_i32_16x16x64_i8 v[142:145], v[206:209], v[166:169], v[142:145]
	v_mfma_i32_16x16x64_i8 v[138:141], v[214:217], v[166:169], v[138:141]
	v_mfma_i32_16x16x64_i8 v[126:129], v[206:209], v[174:177], v[126:129]
	v_mfma_i32_16x16x64_i8 v[122:125], v[214:217], v[174:177], v[122:125]
	v_mfma_i32_16x16x64_i8 v[110:113], v[206:209], v[182:185], v[110:113]
	v_mfma_i32_16x16x64_i8 v[106:109], v[214:217], v[182:185], v[106:109]
	v_mfma_i32_16x16x64_i8 v[94:97], v[206:209], v[198:201], v[94:97]
	v_mfma_i32_16x16x64_i8 v[90:93], v[214:217], v[198:201], v[90:93]
	s_mov_b32 m0, s60
	s_barrier
	ds_read_b128 v[162:165], v194 offset:49152
	ds_read_b128 v[166:169], v194 offset:50176
	ds_read_b128 v[170:173], v194 offset:51200
	ds_read_b128 v[174:177], v194 offset:52224
	ds_read_b128 v[178:181], v194 offset:53248
	ds_read_b128 v[182:185], v194 offset:54272
	ds_read_b128 v[186:189], v194 offset:55296
	ds_read_b128 v[198:201], v194 offset:56320
	s_add_u32 s98, s46, 0x80
	s_addc_u32 s99, s47, 0
	global_load_lds_dwordx4 v146, s[98:99]
	s_mov_b32 m0, s61
	s_nop 0
	global_load_lds_dwordx4 v150, s[98:99]
	s_waitcnt vmcnt(10)
	s_barrier
	s_waitcnt lgkmcnt(0)
	v_mfma_i32_16x16x64_i8 v[70:73], v[58:61], v[162:165], v[70:73]
	v_mfma_i32_16x16x64_i8 v[66:69], v[74:77], v[162:165], v[66:69]
	v_mfma_i32_16x16x64_i8 v[54:57], v[58:61], v[170:173], v[54:57]
	v_mfma_i32_16x16x64_i8 v[50:53], v[74:77], v[170:173], v[50:53]
	v_mfma_i32_16x16x64_i8 v[22:25], v[58:61], v[178:181], v[22:25]
	v_mfma_i32_16x16x64_i8 v[18:21], v[74:77], v[178:181], v[18:21]
	v_mfma_i32_16x16x64_i8 v[6:9], v[58:61], v[186:189], v[6:9]
	v_mfma_i32_16x16x64_i8 v[2:5], v[74:77], v[186:189], v[2:5]
	v_mfma_i32_16x16x64_i8 v[70:73], v[62:65], v[166:169], v[70:73]
	v_mfma_i32_16x16x64_i8 v[66:69], v[78:81], v[166:169], v[66:69]
	v_mfma_i32_16x16x64_i8 v[54:57], v[62:65], v[174:177], v[54:57]
	v_mfma_i32_16x16x64_i8 v[50:53], v[78:81], v[174:177], v[50:53]
	v_mfma_i32_16x16x64_i8 v[22:25], v[62:65], v[182:185], v[22:25]
	v_mfma_i32_16x16x64_i8 v[18:21], v[78:81], v[182:185], v[18:21]
	v_mfma_i32_16x16x64_i8 v[6:9], v[62:65], v[198:201], v[6:9]
	v_mfma_i32_16x16x64_i8 v[2:5], v[78:81], v[198:201], v[2:5]
	s_barrier
	ds_read_b128 v[232:235], v193
	ds_read_b128 v[236:239], v193 offset:1024
	ds_read_b128 v[240:243], v193 offset:2048
	ds_read_b128 v[244:247], v193 offset:3072
	s_add_u32 s0, s44, 0x44080
	s_addc_u32 s1, s45, 0
	s_add_i32 s10, s11, s54
	s_mov_b32 m0, s10
	s_nop 0
	global_load_lds_dwordx4 v148, s[0:1]
	s_add_i32 m0, s10, 0x2000
	s_nop 0
	global_load_lds_dwordx4 v152, s[0:1]
	s_waitcnt vmcnt(6)
	s_barrier
	v_mfma_i32_16x16x64_i8 v[34:37], v[202:205], v[162:165], v[34:37]
	s_add_i32 s77, s77, 2
	s_add_u32 s72, s72, 0x100
	s_addc_u32 s76, s76, 0
	s_cmp_gt_u32 s77, 13
	s_mov_b64 s[34:35], s[40:41]
	v_mfma_i32_16x16x64_i8 v[78:81], v[206:209], v[166:169], v[34:37]
	v_mfma_i32_16x16x64_i8 v[34:37], v[210:213], v[162:165], v[38:41]
	v_mfma_i32_16x16x64_i8 v[74:77], v[214:217], v[166:169], v[34:37]
	v_mfma_i32_16x16x64_i8 v[34:37], v[202:205], v[170:173], v[42:45]
	v_mfma_i32_16x16x64_i8 v[62:65], v[206:209], v[174:177], v[34:37]
	v_mfma_i32_16x16x64_i8 v[34:37], v[210:213], v[170:173], v[46:49]
	v_mfma_i32_16x16x64_i8 v[30:33], v[202:205], v[178:181], v[30:33]
	v_mfma_i32_16x16x64_i8 v[26:29], v[210:213], v[178:181], v[26:29]
	v_mfma_i32_16x16x64_i8 v[14:17], v[202:205], v[186:189], v[14:17]
	v_mfma_i32_16x16x64_i8 v[10:13], v[210:213], v[186:189], v[10:13]
	v_mfma_i32_16x16x64_i8 v[58:61], v[214:217], v[174:177], v[34:37]
	v_mfma_i32_16x16x64_i8 v[30:33], v[206:209], v[182:185], v[30:33]
	v_mfma_i32_16x16x64_i8 v[26:29], v[214:217], v[182:185], v[26:29]
	v_mfma_i32_16x16x64_i8 v[14:17], v[206:209], v[198:201], v[14:17]
	v_mfma_i32_16x16x64_i8 v[10:13], v[214:217], v[198:201], v[10:13]
	s_cbranch_scc1 .Lkdone_p1c
	s_barrier
	s_branch .LBB0_527

; #define G_STAGE(bufoff, gbase, voff) do { _Pragma("unroll") for (int _i = 0; _i < 2; ++_i) \
;         __builtin_amdgcn_global_load_lds((const unsigned*)((const char*)(gbase) + (voff)[_i]), (LAS unsigned*)(lds + (bufoff) + ldsw + _i * 8192), 16, 0, 0); } while (0)
; #define G_WAIT_V(n) asm volatile("s_waitcnt vmcnt(" #n ")" ::: "memory")
; #define G_WAIT_L(n) asm volatile("s_waitcnt lgkmcnt(" #n ")" ::: "memory")
; #define G_BAR __builtin_amdgcn_s_barrier()
; #define G_SCHED __builtin_amdgcn_sched_barrier(0)
; template <int MODE  , class Epi, class Sched>
; __device__ __forceinline__ void gemm_phase(LAS unsigned char* lds, const GemmDesc g, const Sched& S, const Epi& E) {
;     ...
;         for (int t = 0; t < nt; t += 2) {
;             const bool last = (t == nt - 2);
;             const char* a1 = cA + (size_t)(t + 1) * kstep;
;             const char* a2 = last ? nA : cA + (size_t)(t + 2) * kstep; const char* b2 = last ? nB : cB + (size_t)(t + 2) * kstep;
;             const char* a3 = a2 + kstep; const char* b3 = b2 + kstep;
;             G_LDB(B0, 0, 0); G_SCHED; G_LDA(At, 0, 0); G_STAGE(G_SA(1, 1), a1 + hstepA, voffA);
;             G_WAIT_L(8); G_BAR; G_WAIT_L(0); G_MMA(0, 0, At, B0); G_BAR; G_SCHED;
;             G_LDB(B1, 0, 1); G_STAGE(G_SB(0, 0), b2, voffB);
;             G_BAR; G_WAIT_L(0); G_MMA(0, 1, At, B1); G_BAR;
;             G_LDA(At, 0, 1); G_STAGE(G_SA(0, 0), a2, voffA);
;             G_BAR; G_WAIT_L(0); G_MMA(1, 0, At, B0); G_BAR; G_SCHED;
;             G_STAGE(G_SB(0, 1), b2 + hstepB, voffB);
;             G_WAIT_V(6); G_BAR; G_MMA(1, 1, At, B1); G_BAR;
;             G_LDB(B0, 1, 0); G_SCHED; G_LDA(At, 1, 0); G_STAGE(G_SA(0, 1), a2 + hstepA, voffA);
;             G_WAIT_L(8); G_BAR; G_WAIT_L(0); G_MMA(0, 0, At, B0); G_BAR; G_SCHED;
;             G_LDB(B1, 1, 1); G_STAGE(G_SB(1, 0), b3, voffB);
;             G_BAR; G_WAIT_L(0); G_MMA(0, 1, At, B1); G_BAR;
;             G_LDA(At, 1, 1); G_STAGE(G_SA(1, 0), a3, voffA);
.Lnodb_p1b:
.LBB0_737:
	ds_read_b128 v[2:5], v168
	ds_read_b128 v[6:9], v168 offset:1024
	ds_read_b128 v[10:13], v168 offset:2048
	ds_read_b128 v[14:17], v168 offset:3072
	s_add_u32 s46, s50, 0x100
	s_addc_u32 s47, s51, 0
	s_cmp_eq_u32 s79, 12
	s_cselect_b32 s55, s45, s47
	s_cselect_b32 s54, s44, s46
	s_cselect_b32 s53, s3, s78
	s_cselect_b32 s52, s2, s77
	s_add_u32 s98, s50, 0x44080
	s_addc_u32 s99, s51, 0
	s_add_i32 m0, s62, 0xc000
	ds_read_b128 v[174:177], v169
	ds_read_b128 v[178:181], v169 offset:1024
	ds_read_b128 v[182:185], v169 offset:2048
	ds_read_b128 v[186:189], v169 offset:3072
	ds_read_b128 v[192:195], v169 offset:4096
	ds_read_b128 v[196:199], v169 offset:5120
	ds_read_b128 v[200:203], v169 offset:6144
	ds_read_b128 v[204:207], v169 offset:7168
	global_load_lds_dwordx4 v152, s[98:99]
	s_add_i32 m0, s62, 0xe000
	s_nop 0
	global_load_lds_dwordx4 v148, s[98:99]
	s_waitcnt lgkmcnt(8)
	s_barrier
	s_waitcnt lgkmcnt(0)
	v_mfma_scale_f32_16x16x128_f8f6f4 v[142:145], v[2:9], v[174:181], v[142:145], v170, v170 op_sel_hi:[0,0,0]
	v_mfma_scale_f32_16x16x128_f8f6f4 v[138:141], v[10:17], v[174:181], v[138:141], v170, v170 op_sel_hi:[0,0,0]
	v_mfma_scale_f32_16x16x128_f8f6f4 v[126:129], v[2:9], v[182:189], v[126:129], v170, v170 op_sel_hi:[0,0,0]
	v_mfma_scale_f32_16x16x128_f8f6f4 v[122:125], v[10:17], v[182:189], v[122:125], v170, v170 op_sel_hi:[0,0,0]
	v_mfma_scale_f32_16x16x128_f8f6f4 v[110:113], v[2:9], v[192:199], v[110:113], v170, v170 op_sel_hi:[0,0,0]
	v_mfma_scale_f32_16x16x128_f8f6f4 v[106:109], v[10:17], v[192:199], v[106:109], v170, v170 op_sel_hi:[0,0,0]
	v_mfma_scale_f32_16x16x128_f8f6f4 v[94:97], v[2:9], v[200:207], v[94:97], v170, v170 op_sel_hi:[0,0,0]
	v_mfma_scale_f32_16x16x128_f8f6f4 v[90:93], v[10:17], v[200:207], v[90:93], v170, v170 op_sel_hi:[0,0,0]
	s_barrier
	s_add_i32 s0, s69, s60
	s_mov_b32 m0, s0
	ds_read_b128 v[208:211], v171
	ds_read_b128 v[212:215], v171 offset:1024
	ds_read_b128 v[216:219], v171 offset:2048
	ds_read_b128 v[220:223], v171 offset:3072
	global_load_lds_dwordx4 v150, s[52:53]
	s_add_i32 m0, s0, 0x2000
	s_nop 0
	global_load_lds_dwordx4 v146, s[52:53]
	s_barrier
	s_waitcnt lgkmcnt(0)
	v_mfma_scale_f32_16x16x128_f8f6f4 v[134:137], v[208:215], v[174:181], v[134:137], v170, v170 op_sel_hi:[0,0,0]
	v_mfma_scale_f32_16x16x128_f8f6f4 v[130:133], v[216:223], v[174:181], v[130:133], v170, v170 op_sel_hi:[0,0,0]
	v_mfma_scale_f32_16x16x128_f8f6f4 v[118:121], v[208:215], v[182:189], v[118:121], v170, v170 op_sel_hi:[0,0,0]
	v_mfma_scale_f32_16x16x128_f8f6f4 v[114:117], v[216:223], v[182:189], v[114:117], v170, v170 op_sel_hi:[0,0,0]
	v_mfma_scale_f32_16x16x128_f8f6f4 v[102:105], v[208:215], v[192:199], v[102:105], v170, v170 op_sel_hi:[0,0,0]
	v_mfma_scale_f32_16x16x128_f8f6f4 v[98:101], v[216:223], v[192:199], v[98:101], v170, v170 op_sel_hi:[0,0,0]
	v_mfma_scale_f32_16x16x128_f8f6f4 v[86:89], v[208:215], v[200:207], v[86:89], v170, v170 op_sel_hi:[0,0,0]
	v_mfma_scale_f32_16x16x128_f8f6f4 v[82:85], v[216:223], v[200:207], v[82:85], v170, v170 op_sel_hi:[0,0,0]
	s_mov_b32 m0, s62
	s_barrier
	ds_read_b128 v[174:177], v169 offset:16384
	ds_read_b128 v[178:181], v169 offset:17408
	ds_read_b128 v[182:185], v169 offset:18432
	ds_read_b128 v[186:189], v169 offset:19456
	ds_read_b128 v[192:195], v169 offset:20480
	ds_read_b128 v[196:199], v169 offset:21504
	ds_read_b128 v[200:203], v169 offset:22528
	ds_read_b128 v[204:207], v169 offset:23552
	global_load_lds_dwordx4 v152, s[54:55]
	s_mov_b32 m0, s63
	s_nop 0
	global_load_lds_dwordx4 v148, s[54:55]
	s_barrier
	s_waitcnt lgkmcnt(0)
	v_mfma_scale_f32_16x16x128_f8f6f4 v[78:81], v[2:9], v[174:181], v[78:81], v170, v170 op_sel_hi:[0,0,0]
	v_mfma_scale_f32_16x16x128_f8f6f4 v[74:77], v[10:17], v[174:181], v[74:77], v170, v170 op_sel_hi:[0,0,0]
	v_mfma_scale_f32_16x16x128_f8f6f4 v[62:65], v[2:9], v[182:189], v[62:65], v170, v170 op_sel_hi:[0,0,0]
	v_mfma_scale_f32_16x16x128_f8f6f4 v[58:61], v[10:17], v[182:189], v[58:61], v170, v170 op_sel_hi:[0,0,0]
	v_mfma_scale_f32_16x16x128_f8f6f4 v[46:49], v[2:9], v[192:199], v[46:49], v170, v170 op_sel_hi:[0,0,0]
	v_mfma_scale_f32_16x16x128_f8f6f4 v[42:45], v[10:17], v[192:199], v[42:45], v170, v170 op_sel_hi:[0,0,0]
	v_mfma_scale_f32_16x16x128_f8f6f4 v[30:33], v[2:9], v[200:207], v[30:33], v170, v170 op_sel_hi:[0,0,0]
	v_mfma_scale_f32_16x16x128_f8f6f4 v[26:29], v[10:17], v[200:207], v[26:29], v170, v170 op_sel_hi:[0,0,0]
	s_barrier
	s_add_u32 s0, s52, 0x44000
	s_addc_u32 s1, s53, 0
	s_add_i32 s10, s70, s60
	s_mov_b32 m0, s10
	s_nop 0
	global_load_lds_dwordx4 v150, s[0:1]
	s_add_i32 m0, s10, 0x2000
	s_nop 0
	global_load_lds_dwordx4 v146, s[0:1]
	s_waitcnt vmcnt(6)
	s_barrier
	v_mfma_scale_f32_16x16x128_f8f6f4 v[70:73], v[208:215], v[174:181], v[70:73], v170, v170 op_sel_hi:[0,0,0]
	v_mfma_scale_f32_16x16x128_f8f6f4 v[66:69], v[216:223], v[174:181], v[66:69], v170, v170 op_sel_hi:[0,0,0]
	v_mfma_scale_f32_16x16x128_f8f6f4 v[54:57], v[208:215], v[182:189], v[54:57], v170, v170 op_sel_hi:[0,0,0]
	v_mfma_scale_f32_16x16x128_f8f6f4 v[50:53], v[216:223], v[182:189], v[50:53], v170, v170 op_sel_hi:[0,0,0]
	v_mfma_scale_f32_16x16x128_f8f6f4 v[38:41], v[208:215], v[192:199], v[38:41], v170, v170 op_sel_hi:[0,0,0]
	v_mfma_scale_f32_16x16x128_f8f6f4 v[34:37], v[216:223], v[192:199], v[34:37], v170, v170 op_sel_hi:[0,0,0]
	v_mfma_scale_f32_16x16x128_f8f6f4 v[22:25], v[208:215], v[200:207], v[22:25], v170, v170 op_sel_hi:[0,0,0]
	v_mfma_scale_f32_16x16x128_f8f6f4 v[18:21], v[216:223], v[200:207], v[18:21], v170, v170 op_sel_hi:[0,0,0]
	s_add_i32 s10, 0, 0x18000
	v_add_u32_e32 v14, s10, v166
	s_barrier
; #define G_STAGE(bufoff, gbase, voff) do { _Pragma("unroll") for (int _i = 0; _i < 2; ++_i) \
;         __builtin_amdgcn_global_load_lds((const unsigned*)((const char*)(gbase) + (voff)[_i]), (LAS unsigned*)(lds + (bufoff) + ldsw + _i * 8192), 16, 0, 0); } while (0)
; #define G_WAIT_V(n) asm volatile("s_waitcnt vmcnt(" #n ")" ::: "memory")
; #define G_WAIT_L(n) asm volatile("s_waitcnt lgkmcnt(" #n ")" ::: "memory")
; #define G_BAR __builtin_amdgcn_s_barrier()
; #define G_SCHED __builtin_amdgcn_sched_barrier(0)
; template <int MODE  , class Epi, class Sched>
; __device__ __forceinline__ void gemm_phase(LAS unsigned char* lds, const GemmDesc g, const Sched& S, const Epi& E) {
;     ...
;             G_LDB(B0, 1, 0); G_SCHED; G_LDA(At, 1, 0); G_STAGE(G_SA(0, 1), a2 + hstepA, voffA);
;             G_WAIT_L(8); G_BAR; G_WAIT_L(0); G_MMA(0, 0, At, B0); G_BAR; G_SCHED;
;             G_LDB(B1, 1, 1); G_STAGE(G_SB(1, 0), b3, voffB);
;             G_BAR; G_WAIT_L(0); G_MMA(0, 1, At, B1); G_BAR;
;             G_LDA(At, 1, 1); G_STAGE(G_SA(1, 0), a3, voffA);
;             G_BAR; G_WAIT_L(0); G_MMA(1, 0, At, B0); G_BAR; G_SCHED;
;             G_STAGE(G_SB(1, 1), b3 + hstepB, voffB);
;             G_WAIT_V(6); G_BAR; G_MMA(1, 1, At, B1); G_BAR;
;         }
	ds_read_b128 v[2:5], v14
	ds_read_b128 v[6:9], v14 offset:1024
	ds_read_b128 v[10:13], v14 offset:2048
	ds_read_b128 v[14:17], v14 offset:3072
	s_add_u32 s0, s54, 0x44000
	s_addc_u32 s1, s55, 0
	s_mov_b32 m0, s64
	ds_read_b128 v[174:177], v169 offset:32768
	ds_read_b128 v[178:181], v169 offset:33792
	ds_read_b128 v[182:185], v169 offset:34816
	ds_read_b128 v[186:189], v169 offset:35840
	ds_read_b128 v[192:195], v169 offset:36864
	ds_read_b128 v[196:199], v169 offset:37888
	ds_read_b128 v[200:203], v169 offset:38912
	ds_read_b128 v[204:207], v169 offset:39936
	global_load_lds_dwordx4 v152, s[0:1]
	s_mov_b32 m0, s65
	s_nop 0
	global_load_lds_dwordx4 v148, s[0:1]
	s_waitcnt lgkmcnt(8)
	s_barrier
	s_waitcnt lgkmcnt(0)
	v_mfma_scale_f32_16x16x128_f8f6f4 v[142:145], v[2:9], v[174:181], v[142:145], v170, v170 op_sel_hi:[0,0,0]
	v_mfma_scale_f32_16x16x128_f8f6f4 v[138:141], v[10:17], v[174:181], v[138:141], v170, v170 op_sel_hi:[0,0,0]
	v_mfma_scale_f32_16x16x128_f8f6f4 v[126:129], v[2:9], v[182:189], v[126:129], v170, v170 op_sel_hi:[0,0,0]
	v_mfma_scale_f32_16x16x128_f8f6f4 v[122:125], v[10:17], v[182:189], v[122:125], v170, v170 op_sel_hi:[0,0,0]
	v_mfma_scale_f32_16x16x128_f8f6f4 v[110:113], v[2:9], v[192:199], v[110:113], v170, v170 op_sel_hi:[0,0,0]
	v_mfma_scale_f32_16x16x128_f8f6f4 v[106:109], v[10:17], v[192:199], v[106:109], v170, v170 op_sel_hi:[0,0,0]
	v_mfma_scale_f32_16x16x128_f8f6f4 v[94:97], v[2:9], v[200:207], v[94:97], v170, v170 op_sel_hi:[0,0,0]
	v_mfma_scale_f32_16x16x128_f8f6f4 v[90:93], v[10:17], v[200:207], v[90:93], v170, v170 op_sel_hi:[0,0,0]
	s_barrier
	s_add_i32 s11, 0, 0x1c000
	s_add_i32 s0, s10, s60
	v_add_u32_e32 v173, s11, v166
	s_add_u32 s98, s52, 0x80
	s_addc_u32 s99, s53, 0
	s_mov_b32 m0, s0
	ds_read_b128 v[208:211], v173
	ds_read_b128 v[212:215], v173 offset:1024
	ds_read_b128 v[216:219], v173 offset:2048
	ds_read_b128 v[220:223], v173 offset:3072
	global_load_lds_dwordx4 v150, s[98:99]
	s_add_i32 m0, s0, 0x2000
	s_nop 0
	global_load_lds_dwordx4 v146, s[98:99]
	s_barrier
	s_waitcnt lgkmcnt(0)
	v_mfma_scale_f32_16x16x128_f8f6f4 v[134:137], v[208:215], v[174:181], v[134:137], v170, v170 op_sel_hi:[0,0,0]
	v_mfma_scale_f32_16x16x128_f8f6f4 v[130:133], v[216:223], v[174:181], v[130:133], v170, v170 op_sel_hi:[0,0,0]
	v_mfma_scale_f32_16x16x128_f8f6f4 v[118:121], v[208:215], v[182:189], v[118:121], v170, v170 op_sel_hi:[0,0,0]
	v_mfma_scale_f32_16x16x128_f8f6f4 v[114:117], v[216:223], v[182:189], v[114:117], v170, v170 op_sel_hi:[0,0,0]
	v_mfma_scale_f32_16x16x128_f8f6f4 v[102:105], v[208:215], v[192:199], v[102:105], v170, v170 op_sel_hi:[0,0,0]
	v_mfma_scale_f32_16x16x128_f8f6f4 v[98:101], v[216:223], v[192:199], v[98:101], v170, v170 op_sel_hi:[0,0,0]
	v_mfma_scale_f32_16x16x128_f8f6f4 v[86:89], v[208:215], v[200:207], v[86:89], v170, v170 op_sel_hi:[0,0,0]
	v_mfma_scale_f32_16x16x128_f8f6f4 v[82:85], v[216:223], v[200:207], v[82:85], v170, v170 op_sel_hi:[0,0,0]
	s_mov_b32 m0, s67
	s_add_u32 s98, s54, 0x80
	s_addc_u32 s99, s55, 0
	s_barrier
	ds_read_b128 v[174:177], v169 offset:49152
	ds_read_b128 v[178:181], v169 offset:50176
	ds_read_b128 v[182:185], v169 offset:51200
	ds_read_b128 v[186:189], v169 offset:52224
	ds_read_b128 v[192:195], v169 offset:53248
	ds_read_b128 v[196:199], v169 offset:54272
	ds_read_b128 v[200:203], v169 offset:55296
	ds_read_b128 v[204:207], v169 offset:56320
	global_load_lds_dwordx4 v152, s[98:99]
	s_mov_b32 m0, s68
	s_nop 0
	global_load_lds_dwordx4 v148, s[98:99]
	s_barrier
	s_waitcnt lgkmcnt(0)
	v_mfma_scale_f32_16x16x128_f8f6f4 v[78:81], v[2:9], v[174:181], v[78:81], v170, v170 op_sel_hi:[0,0,0]
	v_mfma_scale_f32_16x16x128_f8f6f4 v[74:77], v[10:17], v[174:181], v[74:77], v170, v170 op_sel_hi:[0,0,0]
	v_mfma_scale_f32_16x16x128_f8f6f4 v[62:65], v[2:9], v[182:189], v[62:65], v170, v170 op_sel_hi:[0,0,0]
	v_mfma_scale_f32_16x16x128_f8f6f4 v[58:61], v[10:17], v[182:189], v[58:61], v170, v170 op_sel_hi:[0,0,0]
	v_mfma_scale_f32_16x16x128_f8f6f4 v[46:49], v[2:9], v[192:199], v[46:49], v170, v170 op_sel_hi:[0,0,0]
	v_mfma_scale_f32_16x16x128_f8f6f4 v[42:45], v[10:17], v[192:199], v[42:45], v170, v170 op_sel_hi:[0,0,0]
	v_mfma_scale_f32_16x16x128_f8f6f4 v[30:33], v[2:9], v[200:207], v[30:33], v170, v170 op_sel_hi:[0,0,0]
	v_mfma_scale_f32_16x16x128_f8f6f4 v[26:29], v[10:17], v[200:207], v[26:29], v170, v170 op_sel_hi:[0,0,0]
	s_barrier
	s_add_u32 s0, s52, 0x44080
	s_addc_u32 s1, s53, 0
	s_add_i32 s10, s11, s60
	s_mov_b32 m0, s10
	s_nop 0
	global_load_lds_dwordx4 v150, s[0:1]
	s_add_i32 m0, s10, 0x2000
	s_nop 0
	global_load_lds_dwordx4 v146, s[0:1]
	s_waitcnt vmcnt(6)
	s_barrier
	v_mfma_scale_f32_16x16x128_f8f6f4 v[70:73], v[208:215], v[174:181], v[70:73], v170, v170 op_sel_hi:[0,0,0]
	s_add_i32 s79, s79, 2
	s_add_u32 s77, s77, 0x100
	s_addc_u32 s78, s78, 0
	s_cmp_gt_u32 s79, 13
	s_mov_b64 s[50:51], s[46:47]
	v_mfma_scale_f32_16x16x128_f8f6f4 v[66:69], v[216:223], v[174:181], v[66:69], v170, v170 op_sel_hi:[0,0,0]
	v_mfma_scale_f32_16x16x128_f8f6f4 v[54:57], v[208:215], v[182:189], v[54:57], v170, v170 op_sel_hi:[0,0,0]
	v_mfma_scale_f32_16x16x128_f8f6f4 v[50:53], v[216:223], v[182:189], v[50:53], v170, v170 op_sel_hi:[0,0,0]
	v_mfma_scale_f32_16x16x128_f8f6f4 v[38:41], v[208:215], v[192:199], v[38:41], v170, v170 op_sel_hi:[0,0,0]
	v_mfma_scale_f32_16x16x128_f8f6f4 v[34:37], v[216:223], v[192:199], v[34:37], v170, v170 op_sel_hi:[0,0,0]
	v_mfma_scale_f32_16x16x128_f8f6f4 v[22:25], v[208:215], v[200:207], v[22:25], v170, v170 op_sel_hi:[0,0,0]
	v_mfma_scale_f32_16x16x128_f8f6f4 v[18:21], v[216:223], v[200:207], v[18:21], v170, v170 op_sel_hi:[0,0,0]
	s_cbranch_scc1 .Lkdone_p1b
	s_barrier
	s_branch .LBB0_737

; #define G_STAGE(bufoff, gbase, voff) do { _Pragma("unroll") for (int _i = 0; _i < 2; ++_i) \
;         __builtin_amdgcn_global_load_lds((const unsigned*)((const char*)(gbase) + (voff)[_i]), (LAS unsigned*)(lds + (bufoff) + ldsw + _i * 8192), 16, 0, 0); } while (0)
; #define G_WAIT_V(n) asm volatile("s_waitcnt vmcnt(" #n ")" ::: "memory")
; #define G_WAIT_L(n) asm volatile("s_waitcnt lgkmcnt(" #n ")" ::: "memory")
; #define G_BAR __builtin_amdgcn_s_barrier()
; #define G_SCHED __builtin_amdgcn_sched_barrier(0)
; template <int MODE  , class Epi, class Sched>
; __device__ __forceinline__ void gemm_phase(LAS unsigned char* lds, const GemmDesc g, const Sched& S, const Epi& E) {
;     ...
;         for (int t = 0; t < nt; t += 2) {
;             const bool last = (t == nt - 2);
;             const char* a1 = cA + (size_t)(t + 1) * kstep;
;             const char* a2 = last ? nA : cA + (size_t)(t + 2) * kstep; const char* b2 = last ? nB : cB + (size_t)(t + 2) * kstep;
;             const char* a3 = a2 + kstep; const char* b3 = b2 + kstep;
;             G_LDB(B0, 0, 0); G_SCHED; G_LDA(At, 0, 0); G_STAGE(G_SA(1, 1), a1 + hstepA, voffA);
;             G_WAIT_L(8); G_BAR; G_WAIT_L(0); G_MMA(0, 0, At, B0); G_BAR; G_SCHED;
;             G_LDB(B1, 0, 1); G_STAGE(G_SB(0, 0), b2, voffB);
;             G_BAR; G_WAIT_L(0); G_MMA(0, 1, At, B1); G_BAR;
;             G_LDA(At, 0, 1); G_STAGE(G_SA(0, 0), a2, voffA);
;             G_BAR; G_WAIT_L(0); G_MMA(1, 0, At, B0); G_BAR; G_SCHED;
;             G_STAGE(G_SB(0, 1), b2 + hstepB, voffB);
;             G_WAIT_V(6); G_BAR; G_MMA(1, 1, At, B1); G_BAR;
.Lnodb_sa:
.LBB0_815:
	v_add_u32_e32 v142, s58, v172
	ds_read_b128 v[130:133], v142
	ds_read_b128 v[134:137], v142 offset:1024
	ds_read_b128 v[138:141], v142 offset:2048
	ds_read_b128 v[142:145], v142 offset:3072
	s_add_u32 s44, s42, 0x100
	s_addc_u32 s45, s43, 0
	s_cmp_eq_u32 s68, 12
	s_cselect_b32 s49, s35, s45
	s_cselect_b32 s48, s34, s44
	s_cselect_b32 s47, s3, s67
	s_cselect_b32 s46, s2, s21
	s_add_u32 s98, s42, 0x84080
	s_addc_u32 s99, s43, 0
	s_add_i32 m0, s52, 0xc000
	ds_read_b128 v[158:161], v174
	ds_read_b128 v[162:165], v174 offset:1024
	ds_read_b128 v[166:169], v174 offset:2048
	ds_read_b128 v[176:179], v174 offset:3072
	ds_read_b128 v[180:183], v174 offset:4096
	ds_read_b128 v[184:187], v174 offset:5120
	ds_read_b128 v[192:195], v174 offset:6144
	ds_read_b128 v[196:199], v174 offset:7168
	global_load_lds_dwordx4 v146, s[98:99]
	s_add_i32 m0, s52, 0xe000
	s_nop 0
	global_load_lds_dwordx4 v150, s[98:99]
	s_waitcnt lgkmcnt(8)
	s_barrier
	s_waitcnt lgkmcnt(0)
	v_mfma_f32_16x16x32_bf16 v[126:129], v[130:133], v[158:161], v[126:129]
	v_mfma_f32_16x16x32_bf16 v[122:125], v[138:141], v[158:161], v[122:125]
	v_mfma_f32_16x16x32_bf16 v[118:121], v[130:133], v[166:169], v[118:121]
	v_mfma_f32_16x16x32_bf16 v[114:117], v[138:141], v[166:169], v[114:117]
	v_mfma_f32_16x16x32_bf16 v[110:113], v[130:133], v[180:183], v[110:113]
	v_mfma_f32_16x16x32_bf16 v[106:109], v[138:141], v[180:183], v[106:109]
	v_mfma_f32_16x16x32_bf16 v[102:105], v[130:133], v[192:195], v[102:105]
	v_mfma_f32_16x16x32_bf16 v[98:101], v[138:141], v[192:195], v[98:101]
	v_mfma_f32_16x16x32_bf16 v[126:129], v[134:137], v[162:165], v[126:129]
	v_mfma_f32_16x16x32_bf16 v[122:125], v[142:145], v[162:165], v[122:125]
	v_mfma_f32_16x16x32_bf16 v[118:121], v[134:137], v[176:179], v[118:121]
	v_mfma_f32_16x16x32_bf16 v[114:117], v[142:145], v[176:179], v[114:117]
	v_mfma_f32_16x16x32_bf16 v[110:113], v[134:137], v[184:187], v[110:113]
	v_mfma_f32_16x16x32_bf16 v[106:109], v[142:145], v[184:187], v[106:109]
	v_mfma_f32_16x16x32_bf16 v[102:105], v[134:137], v[196:199], v[102:105]
	v_mfma_f32_16x16x32_bf16 v[98:101], v[142:145], v[196:199], v[98:101]
	s_barrier
	v_add_u32_e32 v170, s59, v172
	s_add_i32 s0, s58, s51
	ds_read_b128 v[200:203], v170
	ds_read_b128 v[204:207], v170 offset:1024
	ds_read_b128 v[208:211], v170 offset:2048
	ds_read_b128 v[212:215], v170 offset:3072
	s_mov_b32 m0, s0
	s_nop 0
	global_load_lds_dwordx4 v148, s[46:47]
	s_add_i32 m0, s0, 0x2000
	s_nop 0
	global_load_lds_dwordx4 v152, s[46:47]
	s_barrier
	s_waitcnt lgkmcnt(0)
	v_mfma_f32_16x16x32_bf16 v[94:97], v[200:203], v[158:161], v[94:97]
	v_mfma_f32_16x16x32_bf16 v[90:93], v[208:211], v[158:161], v[90:93]
	v_mfma_f32_16x16x32_bf16 v[86:89], v[200:203], v[166:169], v[86:89]
	v_mfma_f32_16x16x32_bf16 v[82:85], v[208:211], v[166:169], v[82:85]
	v_mfma_f32_16x16x32_bf16 v[78:81], v[200:203], v[180:183], v[78:81]
	v_mfma_f32_16x16x32_bf16 v[74:77], v[208:211], v[180:183], v[74:77]
	v_mfma_f32_16x16x32_bf16 v[70:73], v[200:203], v[192:195], v[70:73]
	v_mfma_f32_16x16x32_bf16 v[66:69], v[208:211], v[192:195], v[66:69]
	v_mfma_f32_16x16x32_bf16 v[94:97], v[204:207], v[162:165], v[94:97]
	v_mfma_f32_16x16x32_bf16 v[90:93], v[212:215], v[162:165], v[90:93]
	v_mfma_f32_16x16x32_bf16 v[86:89], v[204:207], v[176:179], v[86:89]
	v_mfma_f32_16x16x32_bf16 v[82:85], v[212:215], v[176:179], v[82:85]
	v_mfma_f32_16x16x32_bf16 v[78:81], v[204:207], v[184:187], v[78:81]
	v_mfma_f32_16x16x32_bf16 v[74:77], v[212:215], v[184:187], v[74:77]
	v_mfma_f32_16x16x32_bf16 v[70:73], v[204:207], v[196:199], v[70:73]
	v_mfma_f32_16x16x32_bf16 v[66:69], v[212:215], v[196:199], v[66:69]
	s_mov_b32 m0, s52
	s_barrier
	ds_read_b128 v[158:161], v174 offset:16384
	ds_read_b128 v[162:165], v174 offset:17408
	ds_read_b128 v[166:169], v174 offset:18432
	ds_read_b128 v[176:179], v174 offset:19456
	ds_read_b128 v[180:183], v174 offset:20480
	ds_read_b128 v[184:187], v174 offset:21504
	ds_read_b128 v[192:195], v174 offset:22528
	ds_read_b128 v[196:199], v174 offset:23552
	global_load_lds_dwordx4 v146, s[48:49]
	s_mov_b32 m0, s53
	s_nop 0
	global_load_lds_dwordx4 v150, s[48:49]
	s_barrier
	s_waitcnt lgkmcnt(0)
	v_mfma_f32_16x16x32_bf16 v[62:65], v[130:133], v[158:161], v[62:65]
	v_mfma_f32_16x16x32_bf16 v[58:61], v[138:141], v[158:161], v[58:61]
	v_mfma_f32_16x16x32_bf16 v[54:57], v[130:133], v[166:169], v[54:57]
	v_mfma_f32_16x16x32_bf16 v[50:53], v[138:141], v[166:169], v[50:53]
	v_mfma_f32_16x16x32_bf16 v[46:49], v[130:133], v[180:183], v[46:49]
	v_mfma_f32_16x16x32_bf16 v[42:45], v[138:141], v[180:183], v[42:45]
	v_mfma_f32_16x16x32_bf16 v[38:41], v[130:133], v[192:195], v[38:41]
	v_mfma_f32_16x16x32_bf16 v[34:37], v[138:141], v[192:195], v[34:37]
	v_mfma_f32_16x16x32_bf16 v[62:65], v[134:137], v[162:165], v[62:65]
	v_mfma_f32_16x16x32_bf16 v[58:61], v[142:145], v[162:165], v[58:61]
	v_mfma_f32_16x16x32_bf16 v[54:57], v[134:137], v[176:179], v[54:57]
	v_mfma_f32_16x16x32_bf16 v[50:53], v[142:145], v[176:179], v[50:53]
	v_mfma_f32_16x16x32_bf16 v[46:49], v[134:137], v[184:187], v[46:49]
	v_mfma_f32_16x16x32_bf16 v[42:45], v[142:145], v[184:187], v[42:45]
	v_mfma_f32_16x16x32_bf16 v[38:41], v[134:137], v[196:199], v[38:41]
	v_mfma_f32_16x16x32_bf16 v[34:37], v[142:145], v[196:199], v[34:37]
	s_barrier
	s_add_u32 s0, s46, 0x84000
	s_addc_u32 s1, s47, 0
	s_add_i32 s10, s59, s51
	s_mov_b32 m0, s10
	s_nop 0
	global_load_lds_dwordx4 v148, s[0:1]
	s_add_i32 m0, s10, 0x2000
	s_nop 0
	global_load_lds_dwordx4 v152, s[0:1]
	s_waitcnt vmcnt(6)
	s_barrier
; #define G_STAGE(bufoff, gbase, voff) do { _Pragma("unroll") for (int _i = 0; _i < 2; ++_i) \
;         __builtin_amdgcn_global_load_lds((const unsigned*)((const char*)(gbase) + (voff)[_i]), (LAS unsigned*)(lds + (bufoff) + ldsw + _i * 8192), 16, 0, 0); } while (0)
; #define G_WAIT_V(n) asm volatile("s_waitcnt vmcnt(" #n ")" ::: "memory")
; #define G_WAIT_L(n) asm volatile("s_waitcnt lgkmcnt(" #n ")" ::: "memory")
; #define G_BAR __builtin_amdgcn_s_barrier()
; #define G_SCHED __builtin_amdgcn_sched_barrier(0)
; template <int MODE  , class Epi, class Sched>
; __device__ __forceinline__ void gemm_phase(LAS unsigned char* lds, const GemmDesc g, const Sched& S, const Epi& E) {
;     ...
;             G_WAIT_V(6); G_BAR; G_MMA(1, 1, At, B1); G_BAR;
;             G_LDB(B0, 1, 0); G_SCHED; G_LDA(At, 1, 0); G_STAGE(G_SA(0, 1), a2 + hstepA, voffA);
;             G_WAIT_L(8); G_BAR; G_WAIT_L(0); G_MMA(0, 0, At, B0); G_BAR; G_SCHED;
;             G_LDB(B1, 1, 1); G_STAGE(G_SB(1, 0), b3, voffB);
;             G_BAR; G_WAIT_L(0); G_MMA(0, 1, At, B1); G_BAR;
;             G_LDA(At, 1, 1); G_STAGE(G_SA(1, 0), a3, voffA);
	v_mfma_f32_16x16x32_bf16 v[30:33], v[200:203], v[158:161], v[30:33]
	v_mfma_f32_16x16x32_bf16 v[26:29], v[208:211], v[158:161], v[26:29]
	v_mfma_f32_16x16x32_bf16 v[22:25], v[200:203], v[166:169], v[22:25]
	v_mfma_f32_16x16x32_bf16 v[18:21], v[208:211], v[166:169], v[18:21]
	v_mfma_f32_16x16x32_bf16 v[14:17], v[200:203], v[180:183], v[14:17]
	v_mfma_f32_16x16x32_bf16 v[10:13], v[208:211], v[180:183], v[10:13]
	v_mfma_f32_16x16x32_bf16 v[6:9], v[200:203], v[192:195], v[6:9]
	v_mfma_f32_16x16x32_bf16 v[2:5], v[208:211], v[192:195], v[2:5]
	v_mfma_f32_16x16x32_bf16 v[30:33], v[204:207], v[162:165], v[30:33]
	v_mfma_f32_16x16x32_bf16 v[26:29], v[212:215], v[162:165], v[26:29]
	v_mfma_f32_16x16x32_bf16 v[22:25], v[204:207], v[176:179], v[22:25]
	v_mfma_f32_16x16x32_bf16 v[18:21], v[212:215], v[176:179], v[18:21]
	v_mfma_f32_16x16x32_bf16 v[14:17], v[204:207], v[184:187], v[14:17]
	v_mfma_f32_16x16x32_bf16 v[10:13], v[212:215], v[184:187], v[10:13]
	v_mfma_f32_16x16x32_bf16 v[6:9], v[204:207], v[196:199], v[6:9]
	v_mfma_f32_16x16x32_bf16 v[2:5], v[212:215], v[196:199], v[2:5]
	s_add_i32 s10, 0, 0x18000
	v_add_u32_e32 v142, s10, v172
	s_barrier
	ds_read_b128 v[130:133], v142
	ds_read_b128 v[134:137], v142 offset:1024
	ds_read_b128 v[138:141], v142 offset:2048
	ds_read_b128 v[142:145], v142 offset:3072
	s_add_u32 s0, s48, 0x84000
	s_addc_u32 s1, s49, 0
	s_mov_b32 m0, s54
	ds_read_b128 v[158:161], v174 offset:32768
	ds_read_b128 v[162:165], v174 offset:33792
	ds_read_b128 v[166:169], v174 offset:34816
	ds_read_b128 v[176:179], v174 offset:35840
	ds_read_b128 v[180:183], v174 offset:36864
	ds_read_b128 v[184:187], v174 offset:37888
	ds_read_b128 v[192:195], v174 offset:38912
	ds_read_b128 v[196:199], v174 offset:39936
	global_load_lds_dwordx4 v146, s[0:1]
	s_mov_b32 m0, s55
	s_nop 0
	global_load_lds_dwordx4 v150, s[0:1]
	s_waitcnt lgkmcnt(8)
	s_barrier
	s_waitcnt lgkmcnt(0)
	v_mfma_f32_16x16x32_bf16 v[126:129], v[130:133], v[158:161], v[126:129]
	v_mfma_f32_16x16x32_bf16 v[122:125], v[138:141], v[158:161], v[122:125]
	v_mfma_f32_16x16x32_bf16 v[118:121], v[130:133], v[166:169], v[118:121]
	v_mfma_f32_16x16x32_bf16 v[114:117], v[138:141], v[166:169], v[114:117]
	v_mfma_f32_16x16x32_bf16 v[110:113], v[130:133], v[180:183], v[110:113]
	v_mfma_f32_16x16x32_bf16 v[106:109], v[138:141], v[180:183], v[106:109]
	v_mfma_f32_16x16x32_bf16 v[102:105], v[130:133], v[192:195], v[102:105]
	v_mfma_f32_16x16x32_bf16 v[98:101], v[138:141], v[192:195], v[98:101]
	v_mfma_f32_16x16x32_bf16 v[126:129], v[134:137], v[162:165], v[126:129]
	v_mfma_f32_16x16x32_bf16 v[122:125], v[142:145], v[162:165], v[122:125]
	v_mfma_f32_16x16x32_bf16 v[118:121], v[134:137], v[176:179], v[118:121]
	v_mfma_f32_16x16x32_bf16 v[114:117], v[142:145], v[176:179], v[114:117]
	v_mfma_f32_16x16x32_bf16 v[110:113], v[134:137], v[184:187], v[110:113]
	v_mfma_f32_16x16x32_bf16 v[106:109], v[142:145], v[184:187], v[106:109]
	v_mfma_f32_16x16x32_bf16 v[102:105], v[134:137], v[196:199], v[102:105]
	v_mfma_f32_16x16x32_bf16 v[98:101], v[142:145], v[196:199], v[98:101]
	s_barrier
	s_add_i32 s11, 0, 0x1c000
	s_add_i32 s0, s10, s51
	v_add_u32_e32 v175, s11, v172
	s_add_u32 s98, s46, 0x80
	s_addc_u32 s99, s47, 0
	s_mov_b32 m0, s0
	ds_read_b128 v[200:203], v175
	ds_read_b128 v[204:207], v175 offset:1024
	ds_read_b128 v[208:211], v175 offset:2048
	ds_read_b128 v[212:215], v175 offset:3072
	global_load_lds_dwordx4 v148, s[98:99]
	s_add_i32 m0, s0, 0x2000
	s_nop 0
	global_load_lds_dwordx4 v152, s[98:99]
	s_barrier
; #define G_STAGE(bufoff, gbase, voff) do { _Pragma("unroll") for (int _i = 0; _i < 2; ++_i) \
;         __builtin_amdgcn_global_load_lds((const unsigned*)((const char*)(gbase) + (voff)[_i]), (LAS unsigned*)(lds + (bufoff) + ldsw + _i * 8192), 16, 0, 0); } while (0)
; #define G_WAIT_V(n) asm volatile("s_waitcnt vmcnt(" #n ")" ::: "memory")
; #define G_WAIT_L(n) asm volatile("s_waitcnt lgkmcnt(" #n ")" ::: "memory")
; #define G_BAR __builtin_amdgcn_s_barrier()
; #define G_SCHED __builtin_amdgcn_sched_barrier(0)
; template <int MODE  , class Epi, class Sched>
; __device__ __forceinline__ void gemm_phase(LAS unsigned char* lds, const GemmDesc g, const Sched& S, const Epi& E) {
;     ...
;             G_LDA(At, 1, 1); G_STAGE(G_SA(1, 0), a3, voffA);
;             G_BAR; G_WAIT_L(0); G_MMA(1, 0, At, B0); G_BAR; G_SCHED;
;             G_STAGE(G_SB(1, 1), b3 + hstepB, voffB);
;             G_WAIT_V(6); G_BAR; G_MMA(1, 1, At, B1); G_BAR;
;         }
	s_waitcnt lgkmcnt(0)
	v_mfma_f32_16x16x32_bf16 v[94:97], v[200:203], v[158:161], v[94:97]
	v_mfma_f32_16x16x32_bf16 v[90:93], v[208:211], v[158:161], v[90:93]
	v_mfma_f32_16x16x32_bf16 v[86:89], v[200:203], v[166:169], v[86:89]
	v_mfma_f32_16x16x32_bf16 v[82:85], v[208:211], v[166:169], v[82:85]
	v_mfma_f32_16x16x32_bf16 v[78:81], v[200:203], v[180:183], v[78:81]
	v_mfma_f32_16x16x32_bf16 v[74:77], v[208:211], v[180:183], v[74:77]
	v_mfma_f32_16x16x32_bf16 v[70:73], v[200:203], v[192:195], v[70:73]
	v_mfma_f32_16x16x32_bf16 v[66:69], v[208:211], v[192:195], v[66:69]
	v_mfma_f32_16x16x32_bf16 v[94:97], v[204:207], v[162:165], v[94:97]
	v_mfma_f32_16x16x32_bf16 v[90:93], v[212:215], v[162:165], v[90:93]
	v_mfma_f32_16x16x32_bf16 v[86:89], v[204:207], v[176:179], v[86:89]
	v_mfma_f32_16x16x32_bf16 v[82:85], v[212:215], v[176:179], v[82:85]
	v_mfma_f32_16x16x32_bf16 v[78:81], v[204:207], v[184:187], v[78:81]
	v_mfma_f32_16x16x32_bf16 v[74:77], v[212:215], v[184:187], v[74:77]
	v_mfma_f32_16x16x32_bf16 v[70:73], v[204:207], v[196:199], v[70:73]
	v_mfma_f32_16x16x32_bf16 v[66:69], v[212:215], v[196:199], v[66:69]
	s_mov_b32 m0, s56
	s_add_u32 s98, s48, 0x80
	s_addc_u32 s99, s49, 0
	s_barrier
	ds_read_b128 v[158:161], v174 offset:49152
	ds_read_b128 v[162:165], v174 offset:50176
	ds_read_b128 v[166:169], v174 offset:51200
	ds_read_b128 v[176:179], v174 offset:52224
	ds_read_b128 v[180:183], v174 offset:53248
	ds_read_b128 v[184:187], v174 offset:54272
	ds_read_b128 v[192:195], v174 offset:55296
	ds_read_b128 v[196:199], v174 offset:56320
	global_load_lds_dwordx4 v146, s[98:99]
	s_mov_b32 m0, s57
	s_nop 0
	global_load_lds_dwordx4 v150, s[98:99]
	s_barrier
	s_waitcnt lgkmcnt(0)
	v_mfma_f32_16x16x32_bf16 v[62:65], v[130:133], v[158:161], v[62:65]
	v_mfma_f32_16x16x32_bf16 v[58:61], v[138:141], v[158:161], v[58:61]
	v_mfma_f32_16x16x32_bf16 v[54:57], v[130:133], v[166:169], v[54:57]
	v_mfma_f32_16x16x32_bf16 v[50:53], v[138:141], v[166:169], v[50:53]
	v_mfma_f32_16x16x32_bf16 v[46:49], v[130:133], v[180:183], v[46:49]
	v_mfma_f32_16x16x32_bf16 v[42:45], v[138:141], v[180:183], v[42:45]
	v_mfma_f32_16x16x32_bf16 v[38:41], v[130:133], v[192:195], v[38:41]
	v_mfma_f32_16x16x32_bf16 v[34:37], v[138:141], v[192:195], v[34:37]
	v_mfma_f32_16x16x32_bf16 v[62:65], v[134:137], v[162:165], v[62:65]
	v_mfma_f32_16x16x32_bf16 v[58:61], v[142:145], v[162:165], v[58:61]
	v_mfma_f32_16x16x32_bf16 v[54:57], v[134:137], v[176:179], v[54:57]
	v_mfma_f32_16x16x32_bf16 v[50:53], v[142:145], v[176:179], v[50:53]
	v_mfma_f32_16x16x32_bf16 v[46:49], v[134:137], v[184:187], v[46:49]
	v_mfma_f32_16x16x32_bf16 v[42:45], v[142:145], v[184:187], v[42:45]
	v_mfma_f32_16x16x32_bf16 v[38:41], v[134:137], v[196:199], v[38:41]
	v_mfma_f32_16x16x32_bf16 v[34:37], v[142:145], v[196:199], v[34:37]
	s_barrier
	s_add_u32 s0, s46, 0x84080
	s_addc_u32 s1, s47, 0
	s_add_i32 s10, s11, s51
	s_mov_b32 m0, s10
	s_nop 0
	global_load_lds_dwordx4 v148, s[0:1]
	s_add_i32 m0, s10, 0x2000
	s_nop 0
	global_load_lds_dwordx4 v152, s[0:1]
	s_waitcnt vmcnt(6)
	s_barrier
	v_mfma_f32_16x16x32_bf16 v[30:33], v[200:203], v[158:161], v[30:33]
	s_add_i32 s68, s68, 2
	s_add_u32 s21, s21, 0x100
	s_addc_u32 s67, s67, 0
	s_cmp_gt_u32 s68, 13
	s_mov_b64 s[42:43], s[44:45]
	v_mfma_f32_16x16x32_bf16 v[26:29], v[208:211], v[158:161], v[26:29]
	v_mfma_f32_16x16x32_bf16 v[22:25], v[200:203], v[166:169], v[22:25]
	v_mfma_f32_16x16x32_bf16 v[18:21], v[208:211], v[166:169], v[18:21]
	v_mfma_f32_16x16x32_bf16 v[14:17], v[200:203], v[180:183], v[14:17]
	v_mfma_f32_16x16x32_bf16 v[10:13], v[208:211], v[180:183], v[10:13]
	v_mfma_f32_16x16x32_bf16 v[6:9], v[200:203], v[192:195], v[6:9]
	v_mfma_f32_16x16x32_bf16 v[2:5], v[208:211], v[192:195], v[2:5]
	v_mfma_f32_16x16x32_bf16 v[30:33], v[204:207], v[162:165], v[30:33]
	v_mfma_f32_16x16x32_bf16 v[26:29], v[212:215], v[162:165], v[26:29]
	v_mfma_f32_16x16x32_bf16 v[22:25], v[204:207], v[176:179], v[22:25]
	v_mfma_f32_16x16x32_bf16 v[18:21], v[212:215], v[176:179], v[18:21]
	v_mfma_f32_16x16x32_bf16 v[14:17], v[204:207], v[184:187], v[14:17]
	v_mfma_f32_16x16x32_bf16 v[10:13], v[212:215], v[184:187], v[10:13]
	v_mfma_f32_16x16x32_bf16 v[6:9], v[204:207], v[196:199], v[6:9]
	v_mfma_f32_16x16x32_bf16 v[2:5], v[212:215], v[196:199], v[2:5]
	s_cbranch_scc1 .Lkdone_sa
	s_barrier
	s_branch .LBB0_815

; #define G_STAGE(bufoff, gbase, voff) do { _Pragma("unroll") for (int _i = 0; _i < 2; ++_i) \
;         __builtin_amdgcn_global_load_lds((const unsigned*)((const char*)(gbase) + (voff)[_i]), (LAS unsigned*)(lds + (bufoff) + ldsw + _i * 8192), 16, 0, 0); } while (0)
; #define G_WAIT_V(n) asm volatile("s_waitcnt vmcnt(" #n ")" ::: "memory")
; #define G_WAIT_L(n) asm volatile("s_waitcnt lgkmcnt(" #n ")" ::: "memory")
; #define G_BAR __builtin_amdgcn_s_barrier()
; #define G_SCHED __builtin_amdgcn_sched_barrier(0)
; template <int MODE  , class Epi, class Sched>
; __device__ __forceinline__ void gemm_phase(LAS unsigned char* lds, const GemmDesc g, const Sched& S, const Epi& E) {
;     ...
;         for (int t = 0; t < nt; t += 2) {
;             const bool last = (t == nt - 2);
;             const char* a1 = cA + (size_t)(t + 1) * kstep;
;             const char* a2 = last ? nA : cA + (size_t)(t + 2) * kstep; const char* b2 = last ? nB : cB + (size_t)(t + 2) * kstep;
;             const char* a3 = a2 + kstep; const char* b3 = b2 + kstep;
;             G_LDB(B0, 0, 0); G_SCHED; G_LDA(At, 0, 0); G_STAGE(G_SA(1, 1), a1 + hstepA, voffA);
;             G_WAIT_L(8); G_BAR; G_WAIT_L(0); G_MMA(0, 0, At, B0); G_BAR; G_SCHED;
;             G_LDB(B1, 0, 1); G_STAGE(G_SB(0, 0), b2, voffB);
;             G_BAR; G_WAIT_L(0); G_MMA(0, 1, At, B1); G_BAR;
;             G_LDA(At, 0, 1); G_STAGE(G_SA(0, 0), a2, voffA);
;             G_BAR; G_WAIT_L(0); G_MMA(1, 0, At, B0); G_BAR; G_SCHED;
;             G_STAGE(G_SB(0, 1), b2 + hstepB, voffB);
;             G_WAIT_V(6); G_BAR; G_MMA(1, 1, At, B1); G_BAR;
.Lnodb_sb:
.LBB0_897:
	v_add_u32_e32 v142, s57, v174
	ds_read_b128 v[130:133], v142
	ds_read_b128 v[134:137], v142 offset:1024
	ds_read_b128 v[138:141], v142 offset:2048
	ds_read_b128 v[142:145], v142 offset:3072
	s_add_u32 s42, s40, 0x100
	s_addc_u32 s43, s41, 0
	s_cmp_eq_u32 s71, 12
	s_cselect_b32 s47, s21, s43
	s_cselect_b32 s46, s20, s42
	s_cselect_b32 s45, s3, s70
	s_cselect_b32 s44, s2, s19
	s_add_u32 s98, s40, 0x84080
	s_addc_u32 s99, s41, 0
	s_add_i32 m0, s50, 0xc000
	ds_read_b128 v[158:161], v176
	ds_read_b128 v[162:165], v176 offset:1024
	ds_read_b128 v[166:169], v176 offset:2048
	ds_read_b128 v[170:173], v176 offset:3072
	ds_read_b128 v[178:181], v176 offset:4096
	ds_read_b128 v[182:185], v176 offset:5120
	ds_read_b128 v[186:189], v176 offset:6144
	ds_read_b128 v[192:195], v176 offset:7168
	global_load_lds_dwordx4 v146, s[98:99]
	s_add_i32 m0, s50, 0xe000
	s_nop 0
	global_load_lds_dwordx4 v150, s[98:99]
	s_waitcnt lgkmcnt(8)
	s_barrier
	s_waitcnt lgkmcnt(0)
	v_mfma_f32_16x16x32_bf16 v[126:129], v[130:133], v[158:161], v[126:129]
	v_mfma_f32_16x16x32_bf16 v[122:125], v[138:141], v[158:161], v[122:125]
	v_mfma_f32_16x16x32_bf16 v[118:121], v[130:133], v[166:169], v[118:121]
	v_mfma_f32_16x16x32_bf16 v[114:117], v[138:141], v[166:169], v[114:117]
	v_mfma_f32_16x16x32_bf16 v[110:113], v[130:133], v[178:181], v[110:113]
	v_mfma_f32_16x16x32_bf16 v[106:109], v[138:141], v[178:181], v[106:109]
	v_mfma_f32_16x16x32_bf16 v[102:105], v[130:133], v[186:189], v[102:105]
	v_mfma_f32_16x16x32_bf16 v[98:101], v[138:141], v[186:189], v[98:101]
	v_mfma_f32_16x16x32_bf16 v[126:129], v[134:137], v[162:165], v[126:129]
	v_mfma_f32_16x16x32_bf16 v[122:125], v[142:145], v[162:165], v[122:125]
	v_mfma_f32_16x16x32_bf16 v[118:121], v[134:137], v[170:173], v[118:121]
	v_mfma_f32_16x16x32_bf16 v[114:117], v[142:145], v[170:173], v[114:117]
	v_mfma_f32_16x16x32_bf16 v[110:113], v[134:137], v[182:185], v[110:113]
	v_mfma_f32_16x16x32_bf16 v[106:109], v[142:145], v[182:185], v[106:109]
	v_mfma_f32_16x16x32_bf16 v[102:105], v[134:137], v[192:195], v[102:105]
	v_mfma_f32_16x16x32_bf16 v[98:101], v[142:145], v[192:195], v[98:101]
	s_barrier
	s_add_i32 s0, s57, s49
	v_add_u32_e32 v177, s58, v174
	s_mov_b32 m0, s0
	ds_read_b128 v[196:199], v177
	ds_read_b128 v[200:203], v177 offset:1024
	ds_read_b128 v[204:207], v177 offset:2048
	ds_read_b128 v[208:211], v177 offset:3072
	global_load_lds_dwordx4 v148, s[44:45]
	s_add_i32 m0, s0, 0x2000
	s_nop 0
	global_load_lds_dwordx4 v152, s[44:45]
	s_barrier
	s_waitcnt lgkmcnt(0)
	v_mfma_f32_16x16x32_bf16 v[94:97], v[196:199], v[158:161], v[94:97]
	v_mfma_f32_16x16x32_bf16 v[90:93], v[204:207], v[158:161], v[90:93]
	v_mfma_f32_16x16x32_bf16 v[86:89], v[196:199], v[166:169], v[86:89]
	v_mfma_f32_16x16x32_bf16 v[82:85], v[204:207], v[166:169], v[82:85]
	v_mfma_f32_16x16x32_bf16 v[78:81], v[196:199], v[178:181], v[78:81]
	v_mfma_f32_16x16x32_bf16 v[74:77], v[204:207], v[178:181], v[74:77]
	v_mfma_f32_16x16x32_bf16 v[70:73], v[196:199], v[186:189], v[70:73]
	v_mfma_f32_16x16x32_bf16 v[66:69], v[204:207], v[186:189], v[66:69]
	v_mfma_f32_16x16x32_bf16 v[94:97], v[200:203], v[162:165], v[94:97]
	v_mfma_f32_16x16x32_bf16 v[90:93], v[208:211], v[162:165], v[90:93]
	v_mfma_f32_16x16x32_bf16 v[86:89], v[200:203], v[170:173], v[86:89]
	v_mfma_f32_16x16x32_bf16 v[82:85], v[208:211], v[170:173], v[82:85]
	v_mfma_f32_16x16x32_bf16 v[78:81], v[200:203], v[182:185], v[78:81]
	v_mfma_f32_16x16x32_bf16 v[74:77], v[208:211], v[182:185], v[74:77]
	v_mfma_f32_16x16x32_bf16 v[70:73], v[200:203], v[192:195], v[70:73]
	v_mfma_f32_16x16x32_bf16 v[66:69], v[208:211], v[192:195], v[66:69]
	s_mov_b32 m0, s50
	s_barrier
	ds_read_b128 v[158:161], v176 offset:16384
	ds_read_b128 v[162:165], v176 offset:17408
	ds_read_b128 v[166:169], v176 offset:18432
	ds_read_b128 v[170:173], v176 offset:19456
	ds_read_b128 v[178:181], v176 offset:20480
	ds_read_b128 v[182:185], v176 offset:21504
	ds_read_b128 v[186:189], v176 offset:22528
	ds_read_b128 v[192:195], v176 offset:23552
	global_load_lds_dwordx4 v146, s[46:47]
	s_mov_b32 m0, s51
	s_nop 0
	global_load_lds_dwordx4 v150, s[46:47]
	s_barrier
	s_waitcnt lgkmcnt(0)
	v_mfma_f32_16x16x32_bf16 v[62:65], v[130:133], v[158:161], v[62:65]
	v_mfma_f32_16x16x32_bf16 v[58:61], v[138:141], v[158:161], v[58:61]
	v_mfma_f32_16x16x32_bf16 v[54:57], v[130:133], v[166:169], v[54:57]
	v_mfma_f32_16x16x32_bf16 v[50:53], v[138:141], v[166:169], v[50:53]
	v_mfma_f32_16x16x32_bf16 v[46:49], v[130:133], v[178:181], v[46:49]
	v_mfma_f32_16x16x32_bf16 v[42:45], v[138:141], v[178:181], v[42:45]
	v_mfma_f32_16x16x32_bf16 v[38:41], v[130:133], v[186:189], v[38:41]
	v_mfma_f32_16x16x32_bf16 v[34:37], v[138:141], v[186:189], v[34:37]
	v_mfma_f32_16x16x32_bf16 v[62:65], v[134:137], v[162:165], v[62:65]
	v_mfma_f32_16x16x32_bf16 v[58:61], v[142:145], v[162:165], v[58:61]
	v_mfma_f32_16x16x32_bf16 v[54:57], v[134:137], v[170:173], v[54:57]
	v_mfma_f32_16x16x32_bf16 v[50:53], v[142:145], v[170:173], v[50:53]
	v_mfma_f32_16x16x32_bf16 v[46:49], v[134:137], v[182:185], v[46:49]
	v_mfma_f32_16x16x32_bf16 v[42:45], v[142:145], v[182:185], v[42:45]
	v_mfma_f32_16x16x32_bf16 v[38:41], v[134:137], v[192:195], v[38:41]
	v_mfma_f32_16x16x32_bf16 v[34:37], v[142:145], v[192:195], v[34:37]
	s_barrier
	s_add_u32 s0, s44, 0x84000
	s_addc_u32 s1, s45, 0
	s_add_i32 s10, s58, s49
	s_mov_b32 m0, s10
	s_nop 0
	global_load_lds_dwordx4 v148, s[0:1]
	s_add_i32 m0, s10, 0x2000
	s_nop 0
	global_load_lds_dwordx4 v152, s[0:1]
	s_waitcnt vmcnt(6)
	s_barrier
; #define G_STAGE(bufoff, gbase, voff) do { _Pragma("unroll") for (int _i = 0; _i < 2; ++_i) \
;         __builtin_amdgcn_global_load_lds((const unsigned*)((const char*)(gbase) + (voff)[_i]), (LAS unsigned*)(lds + (bufoff) + ldsw + _i * 8192), 16, 0, 0); } while (0)
; #define G_WAIT_V(n) asm volatile("s_waitcnt vmcnt(" #n ")" ::: "memory")
; #define G_WAIT_L(n) asm volatile("s_waitcnt lgkmcnt(" #n ")" ::: "memory")
; #define G_BAR __builtin_amdgcn_s_barrier()
; #define G_SCHED __builtin_amdgcn_sched_barrier(0)
; template <int MODE  , class Epi, class Sched>
; __device__ __forceinline__ void gemm_phase(LAS unsigned char* lds, const GemmDesc g, const Sched& S, const Epi& E) {
;     ...
;             G_WAIT_V(6); G_BAR; G_MMA(1, 1, At, B1); G_BAR;
;             G_LDB(B0, 1, 0); G_SCHED; G_LDA(At, 1, 0); G_STAGE(G_SA(0, 1), a2 + hstepA, voffA);
;             G_WAIT_L(8); G_BAR; G_WAIT_L(0); G_MMA(0, 0, At, B0); G_BAR; G_SCHED;
;             G_LDB(B1, 1, 1); G_STAGE(G_SB(1, 0), b3, voffB);
;             G_BAR; G_WAIT_L(0); G_MMA(0, 1, At, B1); G_BAR;
;             G_LDA(At, 1, 1); G_STAGE(G_SA(1, 0), a3, voffA);
	v_mfma_f32_16x16x32_bf16 v[30:33], v[196:199], v[158:161], v[30:33]
	v_mfma_f32_16x16x32_bf16 v[26:29], v[204:207], v[158:161], v[26:29]
	v_mfma_f32_16x16x32_bf16 v[22:25], v[196:199], v[166:169], v[22:25]
	v_mfma_f32_16x16x32_bf16 v[18:21], v[204:207], v[166:169], v[18:21]
	v_mfma_f32_16x16x32_bf16 v[14:17], v[196:199], v[178:181], v[14:17]
	v_mfma_f32_16x16x32_bf16 v[10:13], v[204:207], v[178:181], v[10:13]
	v_mfma_f32_16x16x32_bf16 v[6:9], v[196:199], v[186:189], v[6:9]
	v_mfma_f32_16x16x32_bf16 v[2:5], v[204:207], v[186:189], v[2:5]
	v_mfma_f32_16x16x32_bf16 v[30:33], v[200:203], v[162:165], v[30:33]
	v_mfma_f32_16x16x32_bf16 v[26:29], v[208:211], v[162:165], v[26:29]
	v_mfma_f32_16x16x32_bf16 v[22:25], v[200:203], v[170:173], v[22:25]
	v_mfma_f32_16x16x32_bf16 v[18:21], v[208:211], v[170:173], v[18:21]
	v_mfma_f32_16x16x32_bf16 v[14:17], v[200:203], v[182:185], v[14:17]
	v_mfma_f32_16x16x32_bf16 v[10:13], v[208:211], v[182:185], v[10:13]
	v_mfma_f32_16x16x32_bf16 v[6:9], v[200:203], v[192:195], v[6:9]
	v_mfma_f32_16x16x32_bf16 v[2:5], v[208:211], v[192:195], v[2:5]
	s_add_i32 s10, 0, 0x18000
	v_add_u32_e32 v142, s10, v174
	s_barrier
	ds_read_b128 v[130:133], v142
	ds_read_b128 v[134:137], v142 offset:1024
	ds_read_b128 v[138:141], v142 offset:2048
	ds_read_b128 v[142:145], v142 offset:3072
	s_add_u32 s0, s46, 0x84000
	s_addc_u32 s1, s47, 0
	s_mov_b32 m0, s52
	ds_read_b128 v[158:161], v176 offset:32768
	ds_read_b128 v[162:165], v176 offset:33792
	ds_read_b128 v[166:169], v176 offset:34816
	ds_read_b128 v[170:173], v176 offset:35840
	ds_read_b128 v[178:181], v176 offset:36864
	ds_read_b128 v[182:185], v176 offset:37888
	ds_read_b128 v[186:189], v176 offset:38912
	ds_read_b128 v[192:195], v176 offset:39936
	global_load_lds_dwordx4 v146, s[0:1]
	s_mov_b32 m0, s53
	s_nop 0
	global_load_lds_dwordx4 v150, s[0:1]
	s_waitcnt lgkmcnt(8)
	s_barrier
	s_waitcnt lgkmcnt(0)
	v_mfma_f32_16x16x32_bf16 v[126:129], v[130:133], v[158:161], v[126:129]
	v_mfma_f32_16x16x32_bf16 v[122:125], v[138:141], v[158:161], v[122:125]
	v_mfma_f32_16x16x32_bf16 v[118:121], v[130:133], v[166:169], v[118:121]
	v_mfma_f32_16x16x32_bf16 v[114:117], v[138:141], v[166:169], v[114:117]
	v_mfma_f32_16x16x32_bf16 v[110:113], v[130:133], v[178:181], v[110:113]
	v_mfma_f32_16x16x32_bf16 v[106:109], v[138:141], v[178:181], v[106:109]
	v_mfma_f32_16x16x32_bf16 v[102:105], v[130:133], v[186:189], v[102:105]
	v_mfma_f32_16x16x32_bf16 v[98:101], v[138:141], v[186:189], v[98:101]
	v_mfma_f32_16x16x32_bf16 v[126:129], v[134:137], v[162:165], v[126:129]
	v_mfma_f32_16x16x32_bf16 v[122:125], v[142:145], v[162:165], v[122:125]
	v_mfma_f32_16x16x32_bf16 v[118:121], v[134:137], v[170:173], v[118:121]
	v_mfma_f32_16x16x32_bf16 v[114:117], v[142:145], v[170:173], v[114:117]
	v_mfma_f32_16x16x32_bf16 v[110:113], v[134:137], v[182:185], v[110:113]
	v_mfma_f32_16x16x32_bf16 v[106:109], v[142:145], v[182:185], v[106:109]
	v_mfma_f32_16x16x32_bf16 v[102:105], v[134:137], v[192:195], v[102:105]
	v_mfma_f32_16x16x32_bf16 v[98:101], v[142:145], v[192:195], v[98:101]
	s_barrier
	s_add_i32 s11, 0, 0x1c000
	s_add_i32 s0, s10, s49
	v_add_u32_e32 v177, s11, v174
	s_add_u32 s98, s44, 0x80
	s_addc_u32 s99, s45, 0
	s_mov_b32 m0, s0
	ds_read_b128 v[196:199], v177
	ds_read_b128 v[200:203], v177 offset:1024
	ds_read_b128 v[204:207], v177 offset:2048
	ds_read_b128 v[208:211], v177 offset:3072
	global_load_lds_dwordx4 v148, s[98:99]
	s_add_i32 m0, s0, 0x2000
	s_nop 0
	global_load_lds_dwordx4 v152, s[98:99]
	s_barrier
; #define G_STAGE(bufoff, gbase, voff) do { _Pragma("unroll") for (int _i = 0; _i < 2; ++_i) \
;         __builtin_amdgcn_global_load_lds((const unsigned*)((const char*)(gbase) + (voff)[_i]), (LAS unsigned*)(lds + (bufoff) + ldsw + _i * 8192), 16, 0, 0); } while (0)
; #define G_WAIT_V(n) asm volatile("s_waitcnt vmcnt(" #n ")" ::: "memory")
; #define G_WAIT_L(n) asm volatile("s_waitcnt lgkmcnt(" #n ")" ::: "memory")
; #define G_BAR __builtin_amdgcn_s_barrier()
; #define G_SCHED __builtin_amdgcn_sched_barrier(0)
; template <int MODE  , class Epi, class Sched>
; __device__ __forceinline__ void gemm_phase(LAS unsigned char* lds, const GemmDesc g, const Sched& S, const Epi& E) {
;     ...
;             G_LDA(At, 1, 1); G_STAGE(G_SA(1, 0), a3, voffA);
;             G_BAR; G_WAIT_L(0); G_MMA(1, 0, At, B0); G_BAR; G_SCHED;
;             G_STAGE(G_SB(1, 1), b3 + hstepB, voffB);
;             G_WAIT_V(6); G_BAR; G_MMA(1, 1, At, B1); G_BAR;
;         }
	s_waitcnt lgkmcnt(0)
	v_mfma_f32_16x16x32_bf16 v[94:97], v[196:199], v[158:161], v[94:97]
	v_mfma_f32_16x16x32_bf16 v[90:93], v[204:207], v[158:161], v[90:93]
	v_mfma_f32_16x16x32_bf16 v[86:89], v[196:199], v[166:169], v[86:89]
	v_mfma_f32_16x16x32_bf16 v[82:85], v[204:207], v[166:169], v[82:85]
	v_mfma_f32_16x16x32_bf16 v[78:81], v[196:199], v[178:181], v[78:81]
	v_mfma_f32_16x16x32_bf16 v[74:77], v[204:207], v[178:181], v[74:77]
	v_mfma_f32_16x16x32_bf16 v[70:73], v[196:199], v[186:189], v[70:73]
	v_mfma_f32_16x16x32_bf16 v[66:69], v[204:207], v[186:189], v[66:69]
	v_mfma_f32_16x16x32_bf16 v[94:97], v[200:203], v[162:165], v[94:97]
	v_mfma_f32_16x16x32_bf16 v[90:93], v[208:211], v[162:165], v[90:93]
	v_mfma_f32_16x16x32_bf16 v[86:89], v[200:203], v[170:173], v[86:89]
	v_mfma_f32_16x16x32_bf16 v[82:85], v[208:211], v[170:173], v[82:85]
	v_mfma_f32_16x16x32_bf16 v[78:81], v[200:203], v[182:185], v[78:81]
	v_mfma_f32_16x16x32_bf16 v[74:77], v[208:211], v[182:185], v[74:77]
	v_mfma_f32_16x16x32_bf16 v[70:73], v[200:203], v[192:195], v[70:73]
	v_mfma_f32_16x16x32_bf16 v[66:69], v[208:211], v[192:195], v[66:69]
	s_mov_b32 m0, s54
	s_add_u32 s98, s46, 0x80
	s_addc_u32 s99, s47, 0
	s_barrier
	ds_read_b128 v[158:161], v176 offset:49152
	ds_read_b128 v[162:165], v176 offset:50176
	ds_read_b128 v[166:169], v176 offset:51200
	ds_read_b128 v[170:173], v176 offset:52224
	ds_read_b128 v[178:181], v176 offset:53248
	ds_read_b128 v[182:185], v176 offset:54272
	ds_read_b128 v[186:189], v176 offset:55296
	ds_read_b128 v[192:195], v176 offset:56320
	global_load_lds_dwordx4 v146, s[98:99]
	s_mov_b32 m0, s55
	s_nop 0
	global_load_lds_dwordx4 v150, s[98:99]
	s_barrier
	s_waitcnt lgkmcnt(0)
	v_mfma_f32_16x16x32_bf16 v[62:65], v[130:133], v[158:161], v[62:65]
	v_mfma_f32_16x16x32_bf16 v[58:61], v[138:141], v[158:161], v[58:61]
	v_mfma_f32_16x16x32_bf16 v[54:57], v[130:133], v[166:169], v[54:57]
	v_mfma_f32_16x16x32_bf16 v[50:53], v[138:141], v[166:169], v[50:53]
	v_mfma_f32_16x16x32_bf16 v[46:49], v[130:133], v[178:181], v[46:49]
	v_mfma_f32_16x16x32_bf16 v[42:45], v[138:141], v[178:181], v[42:45]
	v_mfma_f32_16x16x32_bf16 v[38:41], v[130:133], v[186:189], v[38:41]
	v_mfma_f32_16x16x32_bf16 v[34:37], v[138:141], v[186:189], v[34:37]
	v_mfma_f32_16x16x32_bf16 v[62:65], v[134:137], v[162:165], v[62:65]
	v_mfma_f32_16x16x32_bf16 v[58:61], v[142:145], v[162:165], v[58:61]
	v_mfma_f32_16x16x32_bf16 v[54:57], v[134:137], v[170:173], v[54:57]
	v_mfma_f32_16x16x32_bf16 v[50:53], v[142:145], v[170:173], v[50:53]
	v_mfma_f32_16x16x32_bf16 v[46:49], v[134:137], v[182:185], v[46:49]
	v_mfma_f32_16x16x32_bf16 v[42:45], v[142:145], v[182:185], v[42:45]
	v_mfma_f32_16x16x32_bf16 v[38:41], v[134:137], v[192:195], v[38:41]
	v_mfma_f32_16x16x32_bf16 v[34:37], v[142:145], v[192:195], v[34:37]
	s_barrier
	s_add_u32 s0, s44, 0x84080
	s_addc_u32 s1, s45, 0
	s_add_i32 s10, s11, s49
	s_mov_b32 m0, s10
	s_nop 0
	global_load_lds_dwordx4 v148, s[0:1]
	s_add_i32 m0, s10, 0x2000
	s_nop 0
	global_load_lds_dwordx4 v152, s[0:1]
	s_waitcnt vmcnt(6)
	s_barrier
	v_mfma_f32_16x16x32_bf16 v[30:33], v[196:199], v[158:161], v[30:33]
	s_add_i32 s71, s71, 2
	s_add_u32 s19, s19, 0x100
	s_addc_u32 s70, s70, 0
	s_cmp_gt_u32 s71, 13
	s_mov_b64 s[40:41], s[42:43]
	v_mfma_f32_16x16x32_bf16 v[26:29], v[204:207], v[158:161], v[26:29]
	v_mfma_f32_16x16x32_bf16 v[22:25], v[196:199], v[166:169], v[22:25]
	v_mfma_f32_16x16x32_bf16 v[18:21], v[204:207], v[166:169], v[18:21]
	v_mfma_f32_16x16x32_bf16 v[14:17], v[196:199], v[178:181], v[14:17]
	v_mfma_f32_16x16x32_bf16 v[10:13], v[204:207], v[178:181], v[10:13]
	v_mfma_f32_16x16x32_bf16 v[6:9], v[196:199], v[186:189], v[6:9]
	v_mfma_f32_16x16x32_bf16 v[2:5], v[204:207], v[186:189], v[2:5]
	v_mfma_f32_16x16x32_bf16 v[30:33], v[200:203], v[162:165], v[30:33]
	v_mfma_f32_16x16x32_bf16 v[26:29], v[208:211], v[162:165], v[26:29]
	v_mfma_f32_16x16x32_bf16 v[22:25], v[200:203], v[170:173], v[22:25]
	v_mfma_f32_16x16x32_bf16 v[18:21], v[208:211], v[170:173], v[18:21]
	v_mfma_f32_16x16x32_bf16 v[14:17], v[200:203], v[182:185], v[14:17]
	v_mfma_f32_16x16x32_bf16 v[10:13], v[208:211], v[182:185], v[10:13]
	v_mfma_f32_16x16x32_bf16 v[6:9], v[200:203], v[192:195], v[6:9]
	v_mfma_f32_16x16x32_bf16 v[2:5], v[208:211], v[192:195], v[2:5]
	s_cbranch_scc1 .Lkdone_sb
	s_barrier
	s_branch .LBB0_897

; #define G_STAGE(bufoff, gbase, voff) do { _Pragma("unroll") for (int _i = 0; _i < 2; ++_i) \
;         __builtin_amdgcn_global_load_lds((const unsigned*)((const char*)(gbase) + (voff)[_i]), (LAS unsigned*)(lds + (bufoff) + ldsw + _i * 8192), 16, 0, 0); } while (0)
; #define G_WAIT_V(n) asm volatile("s_waitcnt vmcnt(" #n ")" ::: "memory")
; #define G_WAIT_L(n) asm volatile("s_waitcnt lgkmcnt(" #n ")" ::: "memory")
; #define G_BAR __builtin_amdgcn_s_barrier()
; #define G_SCHED __builtin_amdgcn_sched_barrier(0)
; template <int MODE  , class Epi, class Sched>
; __device__ __forceinline__ void gemm_phase(LAS unsigned char* lds, const GemmDesc g, const Sched& S, const Epi& E) {
;     ...
;         for (int t = 0; t < nt; t += 2) {
;             const bool last = (t == nt - 2);
;             const char* a1 = cA + (size_t)(t + 1) * kstep;
;             const char* a2 = last ? nA : cA + (size_t)(t + 2) * kstep; const char* b2 = last ? nB : cB + (size_t)(t + 2) * kstep;
;             const char* a3 = a2 + kstep; const char* b3 = b2 + kstep;
;             G_LDB(B0, 0, 0); G_SCHED; G_LDA(At, 0, 0); G_STAGE(G_SA(1, 1), a1 + hstepA, voffA);
;             G_WAIT_L(8); G_BAR; G_WAIT_L(0); G_MMA(0, 0, At, B0); G_BAR; G_SCHED;
;             G_LDB(B1, 0, 1); G_STAGE(G_SB(0, 0), b2, voffB);
;             G_BAR; G_WAIT_L(0); G_MMA(0, 1, At, B1); G_BAR;
;             G_LDA(At, 0, 1); G_STAGE(G_SA(0, 0), a2, voffA);
;             G_BAR; G_WAIT_L(0); G_MMA(1, 0, At, B0); G_BAR; G_SCHED;
;             G_STAGE(G_SB(0, 1), b2 + hstepB, voffB);
;             G_WAIT_V(6); G_BAR; G_MMA(1, 1, At, B1); G_BAR;
.Lnodb_sc:
.LBB0_987:
	v_add_u32_e32 v145, s50, v142
	ds_read_b128 v[146:149], v145
	ds_read_b128 v[150:153], v145 offset:1024
	ds_read_b128 v[154:157], v145 offset:2048
	ds_read_b128 v[158:161], v145 offset:3072
	s_add_u32 s34, s20, 0x100
	s_addc_u32 s35, s21, 0
	s_cmp_eq_u32 s60, 12
	s_cselect_b32 s43, s17, s35
	s_cselect_b32 s42, s16, s34
	s_cselect_b32 s41, s3, s59
	s_cselect_b32 s40, s2, s15
	s_add_u32 s98, s20, 0x84080
	s_addc_u32 s99, s21, 0
	s_add_i32 m0, s44, 0xc000
	ds_read_b128 v[162:165], v144
	ds_read_b128 v[166:169], v144 offset:1024
	ds_read_b128 v[170:173], v144 offset:2048
	ds_read_b128 v[174:177], v144 offset:3072
	ds_read_b128 v[178:181], v144 offset:4096
	ds_read_b128 v[182:185], v144 offset:5120
	ds_read_b128 v[186:189], v144 offset:6144
	ds_read_b128 v[192:195], v144 offset:7168
	global_load_lds_dwordx4 v130, s[98:99]
	s_add_i32 m0, s44, 0xe000
	s_nop 0
	global_load_lds_dwordx4 v134, s[98:99]
	s_waitcnt lgkmcnt(8)
	s_barrier
	s_waitcnt lgkmcnt(0)
	v_mfma_f32_16x16x32_bf16 v[126:129], v[146:149], v[162:165], v[126:129]
	v_mfma_f32_16x16x32_bf16 v[122:125], v[154:157], v[162:165], v[122:125]
	v_mfma_f32_16x16x32_bf16 v[118:121], v[146:149], v[170:173], v[118:121]
	v_mfma_f32_16x16x32_bf16 v[114:117], v[154:157], v[170:173], v[114:117]
	v_mfma_f32_16x16x32_bf16 v[110:113], v[146:149], v[178:181], v[110:113]
	v_mfma_f32_16x16x32_bf16 v[106:109], v[154:157], v[178:181], v[106:109]
	v_mfma_f32_16x16x32_bf16 v[102:105], v[146:149], v[186:189], v[102:105]
	v_mfma_f32_16x16x32_bf16 v[98:101], v[154:157], v[186:189], v[98:101]
	v_mfma_f32_16x16x32_bf16 v[126:129], v[150:153], v[166:169], v[126:129]
	v_mfma_f32_16x16x32_bf16 v[122:125], v[158:161], v[166:169], v[122:125]
	v_mfma_f32_16x16x32_bf16 v[118:121], v[150:153], v[174:177], v[118:121]
	v_mfma_f32_16x16x32_bf16 v[114:117], v[158:161], v[174:177], v[114:117]
	v_mfma_f32_16x16x32_bf16 v[110:113], v[150:153], v[182:185], v[110:113]
	v_mfma_f32_16x16x32_bf16 v[106:109], v[158:161], v[182:185], v[106:109]
	v_mfma_f32_16x16x32_bf16 v[102:105], v[150:153], v[192:195], v[102:105]
	v_mfma_f32_16x16x32_bf16 v[98:101], v[158:161], v[192:195], v[98:101]
	s_barrier
	s_add_i32 s0, s50, s31
	v_add_u32_e32 v145, s51, v142
	s_mov_b32 m0, s0
	ds_read_b128 v[196:199], v145
	ds_read_b128 v[200:203], v145 offset:1024
	ds_read_b128 v[204:207], v145 offset:2048
	ds_read_b128 v[208:211], v145 offset:3072
	global_load_lds_dwordx4 v132, s[40:41]
	s_add_i32 m0, s0, 0x2000
	s_nop 0
	global_load_lds_dwordx4 v136, s[40:41]
	s_barrier
	s_waitcnt lgkmcnt(0)
	v_mfma_f32_16x16x32_bf16 v[94:97], v[196:199], v[162:165], v[94:97]
	v_mfma_f32_16x16x32_bf16 v[90:93], v[204:207], v[162:165], v[90:93]
	v_mfma_f32_16x16x32_bf16 v[86:89], v[196:199], v[170:173], v[86:89]
	v_mfma_f32_16x16x32_bf16 v[82:85], v[204:207], v[170:173], v[82:85]
	v_mfma_f32_16x16x32_bf16 v[78:81], v[196:199], v[178:181], v[78:81]
	v_mfma_f32_16x16x32_bf16 v[74:77], v[204:207], v[178:181], v[74:77]
	v_mfma_f32_16x16x32_bf16 v[70:73], v[196:199], v[186:189], v[70:73]
	v_mfma_f32_16x16x32_bf16 v[66:69], v[204:207], v[186:189], v[66:69]
	v_mfma_f32_16x16x32_bf16 v[94:97], v[200:203], v[166:169], v[94:97]
	v_mfma_f32_16x16x32_bf16 v[90:93], v[208:211], v[166:169], v[90:93]
	v_mfma_f32_16x16x32_bf16 v[86:89], v[200:203], v[174:177], v[86:89]
	v_mfma_f32_16x16x32_bf16 v[82:85], v[208:211], v[174:177], v[82:85]
	v_mfma_f32_16x16x32_bf16 v[78:81], v[200:203], v[182:185], v[78:81]
	v_mfma_f32_16x16x32_bf16 v[74:77], v[208:211], v[182:185], v[74:77]
	v_mfma_f32_16x16x32_bf16 v[70:73], v[200:203], v[192:195], v[70:73]
	v_mfma_f32_16x16x32_bf16 v[66:69], v[208:211], v[192:195], v[66:69]
	s_mov_b32 m0, s44
	s_barrier
	ds_read_b128 v[162:165], v144 offset:16384
	ds_read_b128 v[166:169], v144 offset:17408
	ds_read_b128 v[170:173], v144 offset:18432
	ds_read_b128 v[174:177], v144 offset:19456
	ds_read_b128 v[178:181], v144 offset:20480
	ds_read_b128 v[182:185], v144 offset:21504
	ds_read_b128 v[186:189], v144 offset:22528
	ds_read_b128 v[192:195], v144 offset:23552
	global_load_lds_dwordx4 v130, s[42:43]
	s_mov_b32 m0, s45
	s_nop 0
	global_load_lds_dwordx4 v134, s[42:43]
	s_barrier
	s_waitcnt lgkmcnt(0)
	v_mfma_f32_16x16x32_bf16 v[62:65], v[146:149], v[162:165], v[62:65]
	v_mfma_f32_16x16x32_bf16 v[58:61], v[154:157], v[162:165], v[58:61]
	v_mfma_f32_16x16x32_bf16 v[54:57], v[146:149], v[170:173], v[54:57]
	v_mfma_f32_16x16x32_bf16 v[50:53], v[154:157], v[170:173], v[50:53]
	v_mfma_f32_16x16x32_bf16 v[46:49], v[146:149], v[178:181], v[46:49]
	v_mfma_f32_16x16x32_bf16 v[42:45], v[154:157], v[178:181], v[42:45]
	v_mfma_f32_16x16x32_bf16 v[38:41], v[146:149], v[186:189], v[38:41]
	v_mfma_f32_16x16x32_bf16 v[34:37], v[154:157], v[186:189], v[34:37]
	v_mfma_f32_16x16x32_bf16 v[62:65], v[150:153], v[166:169], v[62:65]
	v_mfma_f32_16x16x32_bf16 v[58:61], v[158:161], v[166:169], v[58:61]
	v_mfma_f32_16x16x32_bf16 v[54:57], v[150:153], v[174:177], v[54:57]
	v_mfma_f32_16x16x32_bf16 v[50:53], v[158:161], v[174:177], v[50:53]
	v_mfma_f32_16x16x32_bf16 v[46:49], v[150:153], v[182:185], v[46:49]
	v_mfma_f32_16x16x32_bf16 v[42:45], v[158:161], v[182:185], v[42:45]
	v_mfma_f32_16x16x32_bf16 v[38:41], v[150:153], v[192:195], v[38:41]
	v_mfma_f32_16x16x32_bf16 v[34:37], v[158:161], v[192:195], v[34:37]
	s_barrier
	s_add_u32 s0, s40, 0x84000
	s_addc_u32 s1, s41, 0
	s_add_i32 s10, s51, s31
	s_mov_b32 m0, s10
	s_nop 0
	global_load_lds_dwordx4 v132, s[0:1]
	s_add_i32 m0, s10, 0x2000
	s_nop 0
	global_load_lds_dwordx4 v136, s[0:1]
	s_waitcnt vmcnt(6)
	s_barrier
; #define G_STAGE(bufoff, gbase, voff) do { _Pragma("unroll") for (int _i = 0; _i < 2; ++_i) \
;         __builtin_amdgcn_global_load_lds((const unsigned*)((const char*)(gbase) + (voff)[_i]), (LAS unsigned*)(lds + (bufoff) + ldsw + _i * 8192), 16, 0, 0); } while (0)
; #define G_WAIT_V(n) asm volatile("s_waitcnt vmcnt(" #n ")" ::: "memory")
; #define G_WAIT_L(n) asm volatile("s_waitcnt lgkmcnt(" #n ")" ::: "memory")
; #define G_BAR __builtin_amdgcn_s_barrier()
; #define G_SCHED __builtin_amdgcn_sched_barrier(0)
; template <int MODE  , class Epi, class Sched>
; __device__ __forceinline__ void gemm_phase(LAS unsigned char* lds, const GemmDesc g, const Sched& S, const Epi& E) {
;     ...
;             G_WAIT_V(6); G_BAR; G_MMA(1, 1, At, B1); G_BAR;
;             G_LDB(B0, 1, 0); G_SCHED; G_LDA(At, 1, 0); G_STAGE(G_SA(0, 1), a2 + hstepA, voffA);
;             G_WAIT_L(8); G_BAR; G_WAIT_L(0); G_MMA(0, 0, At, B0); G_BAR; G_SCHED;
;             G_LDB(B1, 1, 1); G_STAGE(G_SB(1, 0), b3, voffB);
;             G_BAR; G_WAIT_L(0); G_MMA(0, 1, At, B1); G_BAR;
;             G_LDA(At, 1, 1); G_STAGE(G_SA(1, 0), a3, voffA);
	v_mfma_f32_16x16x32_bf16 v[30:33], v[196:199], v[162:165], v[30:33]
	v_mfma_f32_16x16x32_bf16 v[26:29], v[204:207], v[162:165], v[26:29]
	v_mfma_f32_16x16x32_bf16 v[22:25], v[196:199], v[170:173], v[22:25]
	v_mfma_f32_16x16x32_bf16 v[18:21], v[204:207], v[170:173], v[18:21]
	v_mfma_f32_16x16x32_bf16 v[14:17], v[196:199], v[178:181], v[14:17]
	v_mfma_f32_16x16x32_bf16 v[10:13], v[204:207], v[178:181], v[10:13]
	v_mfma_f32_16x16x32_bf16 v[6:9], v[196:199], v[186:189], v[6:9]
	v_mfma_f32_16x16x32_bf16 v[2:5], v[204:207], v[186:189], v[2:5]
	v_mfma_f32_16x16x32_bf16 v[30:33], v[200:203], v[166:169], v[30:33]
	v_mfma_f32_16x16x32_bf16 v[26:29], v[208:211], v[166:169], v[26:29]
	v_mfma_f32_16x16x32_bf16 v[22:25], v[200:203], v[174:177], v[22:25]
	v_mfma_f32_16x16x32_bf16 v[18:21], v[208:211], v[174:177], v[18:21]
	v_mfma_f32_16x16x32_bf16 v[14:17], v[200:203], v[182:185], v[14:17]
	v_mfma_f32_16x16x32_bf16 v[10:13], v[208:211], v[182:185], v[10:13]
	v_mfma_f32_16x16x32_bf16 v[6:9], v[200:203], v[192:195], v[6:9]
	v_mfma_f32_16x16x32_bf16 v[2:5], v[208:211], v[192:195], v[2:5]
	s_add_i32 s10, 0, 0x18000
	v_add_u32_e32 v145, s10, v142
	s_barrier
	ds_read_b128 v[146:149], v145
	ds_read_b128 v[150:153], v145 offset:1024
	ds_read_b128 v[154:157], v145 offset:2048
	ds_read_b128 v[158:161], v145 offset:3072
	s_add_u32 s0, s42, 0x84000
	s_addc_u32 s1, s43, 0
	s_mov_b32 m0, s46
	ds_read_b128 v[162:165], v144 offset:32768
	ds_read_b128 v[166:169], v144 offset:33792
	ds_read_b128 v[170:173], v144 offset:34816
	ds_read_b128 v[174:177], v144 offset:35840
	ds_read_b128 v[178:181], v144 offset:36864
	ds_read_b128 v[182:185], v144 offset:37888
	ds_read_b128 v[186:189], v144 offset:38912
	ds_read_b128 v[192:195], v144 offset:39936
	global_load_lds_dwordx4 v130, s[0:1]
	s_mov_b32 m0, s47
	s_nop 0
	global_load_lds_dwordx4 v134, s[0:1]
	s_waitcnt lgkmcnt(8)
	s_barrier
	s_waitcnt lgkmcnt(0)
	v_mfma_f32_16x16x32_bf16 v[126:129], v[146:149], v[162:165], v[126:129]
	v_mfma_f32_16x16x32_bf16 v[122:125], v[154:157], v[162:165], v[122:125]
	v_mfma_f32_16x16x32_bf16 v[118:121], v[146:149], v[170:173], v[118:121]
	v_mfma_f32_16x16x32_bf16 v[114:117], v[154:157], v[170:173], v[114:117]
	v_mfma_f32_16x16x32_bf16 v[110:113], v[146:149], v[178:181], v[110:113]
	v_mfma_f32_16x16x32_bf16 v[106:109], v[154:157], v[178:181], v[106:109]
	v_mfma_f32_16x16x32_bf16 v[102:105], v[146:149], v[186:189], v[102:105]
	v_mfma_f32_16x16x32_bf16 v[98:101], v[154:157], v[186:189], v[98:101]
	v_mfma_f32_16x16x32_bf16 v[126:129], v[150:153], v[166:169], v[126:129]
	v_mfma_f32_16x16x32_bf16 v[122:125], v[158:161], v[166:169], v[122:125]
	v_mfma_f32_16x16x32_bf16 v[118:121], v[150:153], v[174:177], v[118:121]
	v_mfma_f32_16x16x32_bf16 v[114:117], v[158:161], v[174:177], v[114:117]
	v_mfma_f32_16x16x32_bf16 v[110:113], v[150:153], v[182:185], v[110:113]
	v_mfma_f32_16x16x32_bf16 v[106:109], v[158:161], v[182:185], v[106:109]
	v_mfma_f32_16x16x32_bf16 v[102:105], v[150:153], v[192:195], v[102:105]
	v_mfma_f32_16x16x32_bf16 v[98:101], v[158:161], v[192:195], v[98:101]
	s_barrier
	s_add_i32 s11, 0, 0x1c000
	s_add_i32 s0, s10, s31
	v_add_u32_e32 v145, s11, v142
	s_add_u32 s98, s40, 0x80
	s_addc_u32 s99, s41, 0
	s_mov_b32 m0, s0
	ds_read_b128 v[196:199], v145
	ds_read_b128 v[200:203], v145 offset:1024
	ds_read_b128 v[204:207], v145 offset:2048
	ds_read_b128 v[208:211], v145 offset:3072
	global_load_lds_dwordx4 v132, s[98:99]
	s_add_i32 m0, s0, 0x2000
	s_nop 0
	global_load_lds_dwordx4 v136, s[98:99]
	s_barrier
; #define G_STAGE(bufoff, gbase, voff) do { _Pragma("unroll") for (int _i = 0; _i < 2; ++_i) \
;         __builtin_amdgcn_global_load_lds((const unsigned*)((const char*)(gbase) + (voff)[_i]), (LAS unsigned*)(lds + (bufoff) + ldsw + _i * 8192), 16, 0, 0); } while (0)
; #define G_WAIT_V(n) asm volatile("s_waitcnt vmcnt(" #n ")" ::: "memory")
; #define G_WAIT_L(n) asm volatile("s_waitcnt lgkmcnt(" #n ")" ::: "memory")
; #define G_BAR __builtin_amdgcn_s_barrier()
; #define G_SCHED __builtin_amdgcn_sched_barrier(0)
; template <int MODE  , class Epi, class Sched>
; __device__ __forceinline__ void gemm_phase(LAS unsigned char* lds, const GemmDesc g, const Sched& S, const Epi& E) {
;     ...
;             G_LDA(At, 1, 1); G_STAGE(G_SA(1, 0), a3, voffA);
;             G_BAR; G_WAIT_L(0); G_MMA(1, 0, At, B0); G_BAR; G_SCHED;
;             G_STAGE(G_SB(1, 1), b3 + hstepB, voffB);
;             G_WAIT_V(6); G_BAR; G_MMA(1, 1, At, B1); G_BAR;
;         }
	s_waitcnt lgkmcnt(0)
	v_mfma_f32_16x16x32_bf16 v[94:97], v[196:199], v[162:165], v[94:97]
	v_mfma_f32_16x16x32_bf16 v[90:93], v[204:207], v[162:165], v[90:93]
	v_mfma_f32_16x16x32_bf16 v[86:89], v[196:199], v[170:173], v[86:89]
	v_mfma_f32_16x16x32_bf16 v[82:85], v[204:207], v[170:173], v[82:85]
	v_mfma_f32_16x16x32_bf16 v[78:81], v[196:199], v[178:181], v[78:81]
	v_mfma_f32_16x16x32_bf16 v[74:77], v[204:207], v[178:181], v[74:77]
	v_mfma_f32_16x16x32_bf16 v[70:73], v[196:199], v[186:189], v[70:73]
	v_mfma_f32_16x16x32_bf16 v[66:69], v[204:207], v[186:189], v[66:69]
	v_mfma_f32_16x16x32_bf16 v[94:97], v[200:203], v[166:169], v[94:97]
	v_mfma_f32_16x16x32_bf16 v[90:93], v[208:211], v[166:169], v[90:93]
	v_mfma_f32_16x16x32_bf16 v[86:89], v[200:203], v[174:177], v[86:89]
	v_mfma_f32_16x16x32_bf16 v[82:85], v[208:211], v[174:177], v[82:85]
	v_mfma_f32_16x16x32_bf16 v[78:81], v[200:203], v[182:185], v[78:81]
	v_mfma_f32_16x16x32_bf16 v[74:77], v[208:211], v[182:185], v[74:77]
	v_mfma_f32_16x16x32_bf16 v[70:73], v[200:203], v[192:195], v[70:73]
	v_mfma_f32_16x16x32_bf16 v[66:69], v[208:211], v[192:195], v[66:69]
	s_mov_b32 m0, s48
	s_add_u32 s98, s42, 0x80
	s_addc_u32 s99, s43, 0
	s_barrier
	ds_read_b128 v[162:165], v144 offset:49152
	ds_read_b128 v[166:169], v144 offset:50176
	ds_read_b128 v[170:173], v144 offset:51200
	ds_read_b128 v[174:177], v144 offset:52224
	ds_read_b128 v[178:181], v144 offset:53248
	ds_read_b128 v[182:185], v144 offset:54272
	ds_read_b128 v[186:189], v144 offset:55296
	ds_read_b128 v[192:195], v144 offset:56320
	global_load_lds_dwordx4 v130, s[98:99]
	s_mov_b32 m0, s49
	s_nop 0
	global_load_lds_dwordx4 v134, s[98:99]
	s_barrier
	s_waitcnt lgkmcnt(0)
	v_mfma_f32_16x16x32_bf16 v[62:65], v[146:149], v[162:165], v[62:65]
	v_mfma_f32_16x16x32_bf16 v[58:61], v[154:157], v[162:165], v[58:61]
	v_mfma_f32_16x16x32_bf16 v[54:57], v[146:149], v[170:173], v[54:57]
	v_mfma_f32_16x16x32_bf16 v[50:53], v[154:157], v[170:173], v[50:53]
	v_mfma_f32_16x16x32_bf16 v[46:49], v[146:149], v[178:181], v[46:49]
	v_mfma_f32_16x16x32_bf16 v[42:45], v[154:157], v[178:181], v[42:45]
	v_mfma_f32_16x16x32_bf16 v[38:41], v[146:149], v[186:189], v[38:41]
	v_mfma_f32_16x16x32_bf16 v[34:37], v[154:157], v[186:189], v[34:37]
	v_mfma_f32_16x16x32_bf16 v[62:65], v[150:153], v[166:169], v[62:65]
	v_mfma_f32_16x16x32_bf16 v[58:61], v[158:161], v[166:169], v[58:61]
	v_mfma_f32_16x16x32_bf16 v[54:57], v[150:153], v[174:177], v[54:57]
	v_mfma_f32_16x16x32_bf16 v[50:53], v[158:161], v[174:177], v[50:53]
	v_mfma_f32_16x16x32_bf16 v[46:49], v[150:153], v[182:185], v[46:49]
	v_mfma_f32_16x16x32_bf16 v[42:45], v[158:161], v[182:185], v[42:45]
	v_mfma_f32_16x16x32_bf16 v[38:41], v[150:153], v[192:195], v[38:41]
	v_mfma_f32_16x16x32_bf16 v[34:37], v[158:161], v[192:195], v[34:37]
	s_barrier
	s_add_u32 s0, s40, 0x84080
	s_addc_u32 s1, s41, 0
	s_add_i32 s10, s11, s31
	s_mov_b32 m0, s10
	s_nop 0
	global_load_lds_dwordx4 v132, s[0:1]
	s_add_i32 m0, s10, 0x2000
	s_nop 0
	global_load_lds_dwordx4 v136, s[0:1]
	s_waitcnt vmcnt(6)
	s_barrier
	v_mfma_f32_16x16x32_bf16 v[30:33], v[196:199], v[162:165], v[30:33]
	s_add_i32 s60, s60, 2
	s_add_u32 s15, s15, 0x100
	s_addc_u32 s59, s59, 0
	s_cmp_gt_u32 s60, 13
	s_mov_b64 s[20:21], s[34:35]
	v_mfma_f32_16x16x32_bf16 v[26:29], v[204:207], v[162:165], v[26:29]
	v_mfma_f32_16x16x32_bf16 v[22:25], v[196:199], v[170:173], v[22:25]
	v_mfma_f32_16x16x32_bf16 v[18:21], v[204:207], v[170:173], v[18:21]
	v_mfma_f32_16x16x32_bf16 v[14:17], v[196:199], v[178:181], v[14:17]
	v_mfma_f32_16x16x32_bf16 v[10:13], v[204:207], v[178:181], v[10:13]
	v_mfma_f32_16x16x32_bf16 v[6:9], v[196:199], v[186:189], v[6:9]
	v_mfma_f32_16x16x32_bf16 v[2:5], v[204:207], v[186:189], v[2:5]
	v_mfma_f32_16x16x32_bf16 v[30:33], v[200:203], v[166:169], v[30:33]
	v_mfma_f32_16x16x32_bf16 v[26:29], v[208:211], v[166:169], v[26:29]
	v_mfma_f32_16x16x32_bf16 v[22:25], v[200:203], v[174:177], v[22:25]
	v_mfma_f32_16x16x32_bf16 v[18:21], v[208:211], v[174:177], v[18:21]
	v_mfma_f32_16x16x32_bf16 v[14:17], v[200:203], v[182:185], v[14:17]
	v_mfma_f32_16x16x32_bf16 v[10:13], v[208:211], v[182:185], v[10:13]
	v_mfma_f32_16x16x32_bf16 v[6:9], v[200:203], v[192:195], v[6:9]
	v_mfma_f32_16x16x32_bf16 v[2:5], v[208:211], v[192:195], v[2:5]
	s_cbranch_scc1 .Lkdone_sc
	s_barrier
	s_branch .LBB0_987

; #define G_STAGE(bufoff, gbase, voff) do { _Pragma("unroll") for (int _i = 0; _i < 2; ++_i) \
;         __builtin_amdgcn_global_load_lds((const unsigned*)((const char*)(gbase) + (voff)[_i]), (LAS unsigned*)(lds + (bufoff) + ldsw + _i * 8192), 16, 0, 0); } while (0)
; #define G_WAIT_V(n) asm volatile("s_waitcnt vmcnt(" #n ")" ::: "memory")
; #define G_WAIT_L(n) asm volatile("s_waitcnt lgkmcnt(" #n ")" ::: "memory")
; #define G_BAR __builtin_amdgcn_s_barrier()
; #define G_SCHED __builtin_amdgcn_sched_barrier(0)
; template <int MODE  , class Epi, class Sched>
; __device__ __forceinline__ void gemm_phase(LAS unsigned char* lds, const GemmDesc g, const Sched& S, const Epi& E) {
;     ...
;         for (int t = 0; t < nt; t += 2) {
;             const bool last = (t == nt - 2);
;             const char* a1 = cA + (size_t)(t + 1) * kstep;
;             const char* a2 = last ? nA : cA + (size_t)(t + 2) * kstep; const char* b2 = last ? nB : cB + (size_t)(t + 2) * kstep;
;             const char* a3 = a2 + kstep; const char* b3 = b2 + kstep;
;             G_LDB(B0, 0, 0); G_SCHED; G_LDA(At, 0, 0); G_STAGE(G_SA(1, 1), a1 + hstepA, voffA);
;             G_WAIT_L(8); G_BAR; G_WAIT_L(0); G_MMA(0, 0, At, B0); G_BAR; G_SCHED;
;             G_LDB(B1, 0, 1); G_STAGE(G_SB(0, 0), b2, voffB);
;             G_BAR; G_WAIT_L(0); G_MMA(0, 1, At, B1); G_BAR;
;             G_LDA(At, 0, 1); G_STAGE(G_SA(0, 0), a2, voffA);
;             G_BAR; G_WAIT_L(0); G_MMA(1, 0, At, B0); G_BAR; G_SCHED;
;             G_STAGE(G_SB(0, 1), b2 + hstepB, voffB);
;             G_WAIT_V(6); G_BAR; G_MMA(1, 1, At, B1); G_BAR;
.Lnodb_s1a:
.LBB0_1017:
	ds_read_b128 v[130:133], v163
	ds_read_b128 v[134:137], v163 offset:1024
	ds_read_b128 v[154:157], v163 offset:2048
	ds_read_b128 v[170:173], v163 offset:3072
	s_add_u32 s4, s2, 0x100
	s_addc_u32 s5, s3, 0
	s_cmp_eq_u32 s87, 28
	s_cselect_b32 s53, s47, s5
	s_cselect_b32 s52, s46, s4
	s_cselect_b32 s51, s49, s86
	s_cselect_b32 s50, s48, s85
	s_add_u32 s98, s2, 0x84080
	s_addc_u32 s99, s3, 0
	s_add_i32 m0, s58, 0xc000
	ds_read_b128 v[174:177], v164
	ds_read_b128 v[178:181], v164 offset:1024
	ds_read_b128 v[182:185], v164 offset:2048
	ds_read_b128 v[186:189], v164 offset:3072
	ds_read_b128 v[192:195], v164 offset:4096
	ds_read_b128 v[196:199], v164 offset:5120
	ds_read_b128 v[200:203], v164 offset:6144
	ds_read_b128 v[204:207], v164 offset:7168
	global_load_lds_dwordx4 v138, s[98:99]
	s_add_i32 m0, s58, 0xe000
	s_nop 0
	global_load_lds_dwordx4 v142, s[98:99]
	s_waitcnt lgkmcnt(8)
	s_barrier
	s_waitcnt lgkmcnt(0)
	v_mfma_f32_16x16x32_bf16 v[126:129], v[130:133], v[174:177], v[126:129]
	v_mfma_f32_16x16x32_bf16 v[122:125], v[154:157], v[174:177], v[122:125]
	v_mfma_f32_16x16x32_bf16 v[110:113], v[130:133], v[182:185], v[110:113]
	v_mfma_f32_16x16x32_bf16 v[106:109], v[154:157], v[182:185], v[106:109]
	v_mfma_f32_16x16x32_bf16 v[94:97], v[130:133], v[192:195], v[94:97]
	v_mfma_f32_16x16x32_bf16 v[90:93], v[154:157], v[192:195], v[90:93]
	v_mfma_f32_16x16x32_bf16 v[78:81], v[130:133], v[200:203], v[78:81]
	v_mfma_f32_16x16x32_bf16 v[74:77], v[154:157], v[200:203], v[74:77]
	v_mfma_f32_16x16x32_bf16 v[126:129], v[134:137], v[178:181], v[126:129]
	v_mfma_f32_16x16x32_bf16 v[122:125], v[170:173], v[178:181], v[122:125]
	v_mfma_f32_16x16x32_bf16 v[110:113], v[134:137], v[186:189], v[110:113]
	v_mfma_f32_16x16x32_bf16 v[106:109], v[170:173], v[186:189], v[106:109]
	v_mfma_f32_16x16x32_bf16 v[94:97], v[134:137], v[196:199], v[94:97]
	v_mfma_f32_16x16x32_bf16 v[90:93], v[170:173], v[196:199], v[90:93]
	v_mfma_f32_16x16x32_bf16 v[78:81], v[134:137], v[204:207], v[78:81]
	v_mfma_f32_16x16x32_bf16 v[74:77], v[170:173], v[204:207], v[74:77]
	s_barrier
	s_add_i32 s0, s66, s57
	s_mov_b32 m0, s0
	ds_read_b128 v[208:211], v165
	ds_read_b128 v[212:215], v165 offset:1024
	ds_read_b128 v[216:219], v165 offset:2048
	ds_read_b128 v[220:223], v165 offset:3072
	global_load_lds_dwordx4 v140, s[50:51]
	s_add_i32 m0, s0, 0x2000
	s_nop 0
	global_load_lds_dwordx4 v144, s[50:51]
	s_barrier
	s_waitcnt lgkmcnt(0)
	v_mfma_f32_16x16x32_bf16 v[118:121], v[208:211], v[174:177], v[118:121]
	v_mfma_f32_16x16x32_bf16 v[114:117], v[216:219], v[174:177], v[114:117]
	v_mfma_f32_16x16x32_bf16 v[102:105], v[208:211], v[182:185], v[102:105]
	v_mfma_f32_16x16x32_bf16 v[98:101], v[216:219], v[182:185], v[98:101]
	v_mfma_f32_16x16x32_bf16 v[86:89], v[208:211], v[192:195], v[86:89]
	v_mfma_f32_16x16x32_bf16 v[82:85], v[216:219], v[192:195], v[82:85]
	v_mfma_f32_16x16x32_bf16 v[70:73], v[208:211], v[200:203], v[70:73]
	v_mfma_f32_16x16x32_bf16 v[66:69], v[216:219], v[200:203], v[66:69]
	v_mfma_f32_16x16x32_bf16 v[118:121], v[212:215], v[178:181], v[118:121]
	v_mfma_f32_16x16x32_bf16 v[114:117], v[220:223], v[178:181], v[114:117]
	v_mfma_f32_16x16x32_bf16 v[102:105], v[212:215], v[186:189], v[102:105]
	v_mfma_f32_16x16x32_bf16 v[98:101], v[220:223], v[186:189], v[98:101]
	v_mfma_f32_16x16x32_bf16 v[86:89], v[212:215], v[196:199], v[86:89]
	v_mfma_f32_16x16x32_bf16 v[82:85], v[220:223], v[196:199], v[82:85]
	v_mfma_f32_16x16x32_bf16 v[70:73], v[212:215], v[204:207], v[70:73]
	v_mfma_f32_16x16x32_bf16 v[66:69], v[220:223], v[204:207], v[66:69]
	s_mov_b32 m0, s58
	s_barrier
	ds_read_b128 v[174:177], v164 offset:16384
	ds_read_b128 v[178:181], v164 offset:17408
	ds_read_b128 v[182:185], v164 offset:18432
	ds_read_b128 v[186:189], v164 offset:19456
	ds_read_b128 v[192:195], v164 offset:20480
	ds_read_b128 v[196:199], v164 offset:21504
	ds_read_b128 v[200:203], v164 offset:22528
	ds_read_b128 v[204:207], v164 offset:23552
	global_load_lds_dwordx4 v138, s[52:53]
	s_mov_b32 m0, s59
	s_nop 0
	global_load_lds_dwordx4 v142, s[52:53]
	s_barrier
	s_waitcnt lgkmcnt(0)
	v_mfma_f32_16x16x32_bf16 v[62:65], v[130:133], v[174:177], v[62:65]
	v_mfma_f32_16x16x32_bf16 v[58:61], v[154:157], v[174:177], v[58:61]
	v_mfma_f32_16x16x32_bf16 v[46:49], v[130:133], v[182:185], v[46:49]
	v_mfma_f32_16x16x32_bf16 v[42:45], v[154:157], v[182:185], v[42:45]
	v_mfma_f32_16x16x32_bf16 v[30:33], v[130:133], v[192:195], v[30:33]
	v_mfma_f32_16x16x32_bf16 v[26:29], v[154:157], v[192:195], v[26:29]
	v_mfma_f32_16x16x32_bf16 v[14:17], v[130:133], v[200:203], v[14:17]
	v_mfma_f32_16x16x32_bf16 v[10:13], v[154:157], v[200:203], v[10:13]
	v_mfma_f32_16x16x32_bf16 v[62:65], v[134:137], v[178:181], v[62:65]
	v_mfma_f32_16x16x32_bf16 v[58:61], v[170:173], v[178:181], v[58:61]
	v_mfma_f32_16x16x32_bf16 v[46:49], v[134:137], v[186:189], v[46:49]
	v_mfma_f32_16x16x32_bf16 v[42:45], v[170:173], v[186:189], v[42:45]
	v_mfma_f32_16x16x32_bf16 v[30:33], v[134:137], v[196:199], v[30:33]
	v_mfma_f32_16x16x32_bf16 v[26:29], v[170:173], v[196:199], v[26:29]
	v_mfma_f32_16x16x32_bf16 v[14:17], v[134:137], v[204:207], v[14:17]
	v_mfma_f32_16x16x32_bf16 v[10:13], v[170:173], v[204:207], v[10:13]
	s_barrier
	s_add_u32 s0, s50, 0x84000
	s_addc_u32 s1, s51, 0
	s_add_i32 s2, s67, s57
	s_mov_b32 m0, s2
	s_nop 0
	global_load_lds_dwordx4 v140, s[0:1]
	s_add_i32 m0, s2, 0x2000
	s_nop 0
	global_load_lds_dwordx4 v144, s[0:1]
	s_waitcnt vmcnt(6)
	s_barrier
; #define G_STAGE(bufoff, gbase, voff) do { _Pragma("unroll") for (int _i = 0; _i < 2; ++_i) \
;         __builtin_amdgcn_global_load_lds((const unsigned*)((const char*)(gbase) + (voff)[_i]), (LAS unsigned*)(lds + (bufoff) + ldsw + _i * 8192), 16, 0, 0); } while (0)
; #define G_WAIT_V(n) asm volatile("s_waitcnt vmcnt(" #n ")" ::: "memory")
; #define G_WAIT_L(n) asm volatile("s_waitcnt lgkmcnt(" #n ")" ::: "memory")
; #define G_BAR __builtin_amdgcn_s_barrier()
; #define G_SCHED __builtin_amdgcn_sched_barrier(0)
; template <int MODE  , class Epi, class Sched>
; __device__ __forceinline__ void gemm_phase(LAS unsigned char* lds, const GemmDesc g, const Sched& S, const Epi& E) {
;     ...
;             G_WAIT_V(6); G_BAR; G_MMA(1, 1, At, B1); G_BAR;
;             G_LDB(B0, 1, 0); G_SCHED; G_LDA(At, 1, 0); G_STAGE(G_SA(0, 1), a2 + hstepA, voffA);
;             G_WAIT_L(8); G_BAR; G_WAIT_L(0); G_MMA(0, 0, At, B0); G_BAR; G_SCHED;
;             G_LDB(B1, 1, 1); G_STAGE(G_SB(1, 0), b3, voffB);
;             G_BAR; G_WAIT_L(0); G_MMA(0, 1, At, B1); G_BAR;
;             G_LDA(At, 1, 1); G_STAGE(G_SA(1, 0), a3, voffA);
	v_mfma_f32_16x16x32_bf16 v[54:57], v[208:211], v[174:177], v[54:57]
	v_mfma_f32_16x16x32_bf16 v[50:53], v[216:219], v[174:177], v[50:53]
	v_mfma_f32_16x16x32_bf16 v[38:41], v[208:211], v[182:185], v[38:41]
	v_mfma_f32_16x16x32_bf16 v[34:37], v[216:219], v[182:185], v[34:37]
	v_mfma_f32_16x16x32_bf16 v[22:25], v[208:211], v[192:195], v[22:25]
	v_mfma_f32_16x16x32_bf16 v[18:21], v[216:219], v[192:195], v[18:21]
	v_mfma_f32_16x16x32_bf16 v[6:9], v[208:211], v[200:203], v[6:9]
	v_mfma_f32_16x16x32_bf16 v[2:5], v[216:219], v[200:203], v[2:5]
	v_mfma_f32_16x16x32_bf16 v[54:57], v[212:215], v[178:181], v[54:57]
	v_mfma_f32_16x16x32_bf16 v[50:53], v[220:223], v[178:181], v[50:53]
	v_mfma_f32_16x16x32_bf16 v[38:41], v[212:215], v[186:189], v[38:41]
	v_mfma_f32_16x16x32_bf16 v[34:37], v[220:223], v[186:189], v[34:37]
	v_mfma_f32_16x16x32_bf16 v[22:25], v[212:215], v[196:199], v[22:25]
	v_mfma_f32_16x16x32_bf16 v[18:21], v[220:223], v[196:199], v[18:21]
	v_mfma_f32_16x16x32_bf16 v[6:9], v[212:215], v[204:207], v[6:9]
	v_mfma_f32_16x16x32_bf16 v[2:5], v[220:223], v[204:207], v[2:5]
	s_add_i32 s2, 0, 0x18000
	v_add_u32_e32 v146, s2, v160
	s_barrier
	ds_read_b128 v[130:133], v146
	ds_read_b128 v[134:137], v146 offset:1024
	ds_read_b128 v[154:157], v146 offset:2048
	ds_read_b128 v[170:173], v146 offset:3072
	s_add_u32 s0, s52, 0x84000
	s_addc_u32 s1, s53, 0
	s_mov_b32 m0, s60
	ds_read_b128 v[174:177], v164 offset:32768
	ds_read_b128 v[178:181], v164 offset:33792
	ds_read_b128 v[182:185], v164 offset:34816
	ds_read_b128 v[186:189], v164 offset:35840
	ds_read_b128 v[192:195], v164 offset:36864
	ds_read_b128 v[196:199], v164 offset:37888
	ds_read_b128 v[200:203], v164 offset:38912
	ds_read_b128 v[204:207], v164 offset:39936
	global_load_lds_dwordx4 v138, s[0:1]
	s_mov_b32 m0, s61
	s_nop 0
	global_load_lds_dwordx4 v142, s[0:1]
	s_waitcnt lgkmcnt(8)
	s_barrier
	s_waitcnt lgkmcnt(0)
	v_mfma_f32_16x16x32_bf16 v[126:129], v[130:133], v[174:177], v[126:129]
	v_mfma_f32_16x16x32_bf16 v[122:125], v[154:157], v[174:177], v[122:125]
	v_mfma_f32_16x16x32_bf16 v[110:113], v[130:133], v[182:185], v[110:113]
	v_mfma_f32_16x16x32_bf16 v[106:109], v[154:157], v[182:185], v[106:109]
	v_mfma_f32_16x16x32_bf16 v[94:97], v[130:133], v[192:195], v[94:97]
	v_mfma_f32_16x16x32_bf16 v[90:93], v[154:157], v[192:195], v[90:93]
	v_mfma_f32_16x16x32_bf16 v[78:81], v[130:133], v[200:203], v[78:81]
	v_mfma_f32_16x16x32_bf16 v[74:77], v[154:157], v[200:203], v[74:77]
	v_mfma_f32_16x16x32_bf16 v[126:129], v[134:137], v[178:181], v[126:129]
	v_mfma_f32_16x16x32_bf16 v[122:125], v[170:173], v[178:181], v[122:125]
	v_mfma_f32_16x16x32_bf16 v[110:113], v[134:137], v[186:189], v[110:113]
	v_mfma_f32_16x16x32_bf16 v[106:109], v[170:173], v[186:189], v[106:109]
	v_mfma_f32_16x16x32_bf16 v[94:97], v[134:137], v[196:199], v[94:97]
	v_mfma_f32_16x16x32_bf16 v[90:93], v[170:173], v[196:199], v[90:93]
	v_mfma_f32_16x16x32_bf16 v[78:81], v[134:137], v[204:207], v[78:81]
	v_mfma_f32_16x16x32_bf16 v[74:77], v[170:173], v[204:207], v[74:77]
	s_barrier
	s_add_i32 s3, 0, 0x1c000
	s_add_i32 s0, s2, s57
	v_add_u32_e32 v146, s3, v160
	s_add_u32 s98, s50, 0x80
	s_addc_u32 s99, s51, 0
	s_mov_b32 m0, s0
	ds_read_b128 v[208:211], v146
	ds_read_b128 v[212:215], v146 offset:1024
	ds_read_b128 v[216:219], v146 offset:2048
	ds_read_b128 v[220:223], v146 offset:3072
	global_load_lds_dwordx4 v140, s[98:99]
	s_add_i32 m0, s0, 0x2000
	s_nop 0
	global_load_lds_dwordx4 v144, s[98:99]
	s_barrier
; #define G_STAGE(bufoff, gbase, voff) do { _Pragma("unroll") for (int _i = 0; _i < 2; ++_i) \
;         __builtin_amdgcn_global_load_lds((const unsigned*)((const char*)(gbase) + (voff)[_i]), (LAS unsigned*)(lds + (bufoff) + ldsw + _i * 8192), 16, 0, 0); } while (0)
; #define G_WAIT_V(n) asm volatile("s_waitcnt vmcnt(" #n ")" ::: "memory")
; #define G_WAIT_L(n) asm volatile("s_waitcnt lgkmcnt(" #n ")" ::: "memory")
; #define G_BAR __builtin_amdgcn_s_barrier()
; #define G_SCHED __builtin_amdgcn_sched_barrier(0)
; template <int MODE  , class Epi, class Sched>
; __device__ __forceinline__ void gemm_phase(LAS unsigned char* lds, const GemmDesc g, const Sched& S, const Epi& E) {
;     ...
;             G_LDA(At, 1, 1); G_STAGE(G_SA(1, 0), a3, voffA);
;             G_BAR; G_WAIT_L(0); G_MMA(1, 0, At, B0); G_BAR; G_SCHED;
;             G_STAGE(G_SB(1, 1), b3 + hstepB, voffB);
;             G_WAIT_V(6); G_BAR; G_MMA(1, 1, At, B1); G_BAR;
;         }
	s_waitcnt lgkmcnt(0)
	v_mfma_f32_16x16x32_bf16 v[118:121], v[208:211], v[174:177], v[118:121]
	v_mfma_f32_16x16x32_bf16 v[114:117], v[216:219], v[174:177], v[114:117]
	v_mfma_f32_16x16x32_bf16 v[102:105], v[208:211], v[182:185], v[102:105]
	v_mfma_f32_16x16x32_bf16 v[98:101], v[216:219], v[182:185], v[98:101]
	v_mfma_f32_16x16x32_bf16 v[86:89], v[208:211], v[192:195], v[86:89]
	v_mfma_f32_16x16x32_bf16 v[82:85], v[216:219], v[192:195], v[82:85]
	v_mfma_f32_16x16x32_bf16 v[70:73], v[208:211], v[200:203], v[70:73]
	v_mfma_f32_16x16x32_bf16 v[66:69], v[216:219], v[200:203], v[66:69]
	v_mfma_f32_16x16x32_bf16 v[118:121], v[212:215], v[178:181], v[118:121]
	v_mfma_f32_16x16x32_bf16 v[114:117], v[220:223], v[178:181], v[114:117]
	v_mfma_f32_16x16x32_bf16 v[102:105], v[212:215], v[186:189], v[102:105]
	v_mfma_f32_16x16x32_bf16 v[98:101], v[220:223], v[186:189], v[98:101]
	v_mfma_f32_16x16x32_bf16 v[86:89], v[212:215], v[196:199], v[86:89]
	v_mfma_f32_16x16x32_bf16 v[82:85], v[220:223], v[196:199], v[82:85]
	v_mfma_f32_16x16x32_bf16 v[70:73], v[212:215], v[204:207], v[70:73]
	v_mfma_f32_16x16x32_bf16 v[66:69], v[220:223], v[204:207], v[66:69]
	s_mov_b32 m0, s64
	s_add_u32 s98, s52, 0x80
	s_addc_u32 s99, s53, 0
	s_barrier
	ds_read_b128 v[174:177], v164 offset:49152
	ds_read_b128 v[178:181], v164 offset:50176
	ds_read_b128 v[182:185], v164 offset:51200
	ds_read_b128 v[186:189], v164 offset:52224
	ds_read_b128 v[192:195], v164 offset:53248
	ds_read_b128 v[196:199], v164 offset:54272
	ds_read_b128 v[200:203], v164 offset:55296
	ds_read_b128 v[204:207], v164 offset:56320
	global_load_lds_dwordx4 v138, s[98:99]
	s_mov_b32 m0, s65
	s_nop 0
	global_load_lds_dwordx4 v142, s[98:99]
	s_barrier
	s_waitcnt lgkmcnt(0)
	v_mfma_f32_16x16x32_bf16 v[62:65], v[130:133], v[174:177], v[62:65]
	v_mfma_f32_16x16x32_bf16 v[58:61], v[154:157], v[174:177], v[58:61]
	v_mfma_f32_16x16x32_bf16 v[46:49], v[130:133], v[182:185], v[46:49]
	v_mfma_f32_16x16x32_bf16 v[42:45], v[154:157], v[182:185], v[42:45]
	v_mfma_f32_16x16x32_bf16 v[30:33], v[130:133], v[192:195], v[30:33]
	v_mfma_f32_16x16x32_bf16 v[26:29], v[154:157], v[192:195], v[26:29]
	v_mfma_f32_16x16x32_bf16 v[14:17], v[130:133], v[200:203], v[14:17]
	v_mfma_f32_16x16x32_bf16 v[10:13], v[154:157], v[200:203], v[10:13]
	v_mfma_f32_16x16x32_bf16 v[62:65], v[134:137], v[178:181], v[62:65]
	v_mfma_f32_16x16x32_bf16 v[58:61], v[170:173], v[178:181], v[58:61]
	v_mfma_f32_16x16x32_bf16 v[46:49], v[134:137], v[186:189], v[46:49]
	v_mfma_f32_16x16x32_bf16 v[42:45], v[170:173], v[186:189], v[42:45]
	v_mfma_f32_16x16x32_bf16 v[30:33], v[134:137], v[196:199], v[30:33]
	v_mfma_f32_16x16x32_bf16 v[26:29], v[170:173], v[196:199], v[26:29]
	v_mfma_f32_16x16x32_bf16 v[14:17], v[134:137], v[204:207], v[14:17]
	v_mfma_f32_16x16x32_bf16 v[10:13], v[170:173], v[204:207], v[10:13]
	s_barrier
	s_add_u32 s0, s50, 0x84080
	s_addc_u32 s1, s51, 0
	s_add_i32 s2, s3, s57
	s_mov_b32 m0, s2
	s_nop 0
	global_load_lds_dwordx4 v140, s[0:1]
	s_add_i32 m0, s2, 0x2000
	s_nop 0
	global_load_lds_dwordx4 v144, s[0:1]
	s_waitcnt vmcnt(6)
	s_barrier
	v_mfma_f32_16x16x32_bf16 v[54:57], v[208:211], v[174:177], v[54:57]
	s_add_i32 s87, s87, 2
	s_add_u32 s85, s85, 0x100
	s_addc_u32 s86, s86, 0
	s_cmp_gt_u32 s87, 29
	s_mov_b64 s[2:3], s[4:5]
	v_mfma_f32_16x16x32_bf16 v[50:53], v[216:219], v[174:177], v[50:53]
	v_mfma_f32_16x16x32_bf16 v[38:41], v[208:211], v[182:185], v[38:41]
	v_mfma_f32_16x16x32_bf16 v[34:37], v[216:219], v[182:185], v[34:37]
	v_mfma_f32_16x16x32_bf16 v[22:25], v[208:211], v[192:195], v[22:25]
	v_mfma_f32_16x16x32_bf16 v[18:21], v[216:219], v[192:195], v[18:21]
	v_mfma_f32_16x16x32_bf16 v[6:9], v[208:211], v[200:203], v[6:9]
	v_mfma_f32_16x16x32_bf16 v[2:5], v[216:219], v[200:203], v[2:5]
	v_mfma_f32_16x16x32_bf16 v[54:57], v[212:215], v[178:181], v[54:57]
	v_mfma_f32_16x16x32_bf16 v[50:53], v[220:223], v[178:181], v[50:53]
	v_mfma_f32_16x16x32_bf16 v[38:41], v[212:215], v[186:189], v[38:41]
	v_mfma_f32_16x16x32_bf16 v[34:37], v[220:223], v[186:189], v[34:37]
	v_mfma_f32_16x16x32_bf16 v[22:25], v[212:215], v[196:199], v[22:25]
	v_mfma_f32_16x16x32_bf16 v[18:21], v[220:223], v[196:199], v[18:21]
	v_mfma_f32_16x16x32_bf16 v[6:9], v[212:215], v[204:207], v[6:9]
	v_mfma_f32_16x16x32_bf16 v[2:5], v[220:223], v[204:207], v[2:5]
	s_cbranch_scc1 .Lkdone_s1a
	s_barrier
	s_branch .LBB0_1017
